# v94 + K-loops: '+128 rows' LDS-DMA addresses derived from the first address plus a constant pair s[100:101] (6 SALU fewer per 2 K-tiles; two more loads in offset:128 form)
# baseline (speedup 1.0000x reference)
; #define PG8_STAGE(bufoff, gbase, voff) do { _Pragma("unroll") for (int _i = 0; _i < 2; ++_i) \
;         __builtin_amdgcn_global_load_lds((const unsigned*)((const char*)(gbase) + (voff)[_i]), (PG8_LAS unsigned*)(lds + (bufoff) + ldsw + _i * 8192), 16, 0, 0); } while (0)
; #define PG8_LDA(dst, b, h) do { _Pragma("unroll") for (int m = 0; m < 4; ++m) _Pragma("unroll") for (int k = 0; k < 2; ++k) dst[m][k] = *(const PG8_LAS bf16x8*)(lds + PG8_SA(b, h) + aoff + m * 2048 + k * 1024); } while (0)
; #define PG8_LDB(dst, b, h) do { _Pragma("unroll") for (int n = 0; n < 2; ++n) _Pragma("unroll") for (int k = 0; k < 2; ++k) dst[n][k] = *(const PG8_LAS bf16x8*)(lds + PG8_SB(b, h) + boff + n * 2048 + k * 1024); } while (0)
; #define PG8_WAIT_V(n) asm volatile("s_waitcnt vmcnt(" #n ")" ::: "memory")
; #define PG8_WAIT_L(n) asm volatile("s_waitcnt lgkmcnt(" #n ")" ::: "memory")
; #define PG8_BAR __builtin_amdgcn_s_barrier()
; #define PG8_SCHED __builtin_amdgcn_sched_barrier(0)
; template <class Epi, class Sched, bool ALIGN_EPI = false, bool SP2 = false>
; __device__ __forceinline__ void gemm_phase(PG8_LAS unsigned char* lds, const Gemm g, const Sched& S, const Epi& E) {
;     ...
;         const bool has_next = S.next(ui + 1, nxt);
;         const char* nA = has_next ? (const char*)g.A + (size_t)nxt.pm * tstep : cA; const char* nB = has_next ? (const char*)g.Bt + (size_t)nxt.pn * tstep : cB;
;         for (int t = 0; t < nt; t += 2) {
;             const bool last = (t == nt - 2);
;             const char* a1 = cA + (size_t)(t + 1) * kstep;
;             const char* a2 = last ? nA : cA + (size_t)(t + 2) * kstep; const char* b2 = last ? nB : cB + (size_t)(t + 2) * kstep;
;             const char* a3 = a2 + kstep; const char* b3 = b2 + kstep;
;             if (last && has_next) S.a_ready(nxt);
;             if constexpr (SP2) {
;             PG8_LDB(B0, 0, 0); PG8_LDB(B1, 0, 1); PG8_SCHED; PG8_LDA(At, 0, 0); PG8_STAGE(PG8_SA(1, 1), a1 + hstep, voffA);
;             PG8_WAIT_V(8); PG8_WAIT_L(0); PG8_BAR; PG8_MMA(0, 0, At, B0); PG8_MMA(0, 1, At, B1); PG8_BAR; PG8_SCHED;
;             PG8_LDA(At, 0, 1); PG8_STAGE(PG8_SB(0, 0), b2, voffB); PG8_STAGE(PG8_SB(0, 1), b2 + hstep, voffB); PG8_STAGE(PG8_SA(0, 0), a2, voffA);
;             PG8_WAIT_V(8); PG8_WAIT_L(0); PG8_BAR; PG8_MMA(1, 0, At, B0); PG8_MMA(1, 1, At, B1); PG8_BAR; PG8_SCHED;
.LBB0_99:
	s_ashr_i32 s21, s20, 31
	s_lshl_b64 s[24:25], s[20:21], 19
	s_add_u32 s24, s35, s24
	s_addc_u32 s25, s38, s25
	s_and_b64 s[26:27], s[4:5], exec
	s_cselect_b32 s3, s25, s9
	s_cselect_b32 s7, s24, s8
	s_ashr_i32 s23, s22, 31
	s_lshl_b64 s[26:27], s[22:23], 19
	s_add_u32 s26, s39, s26
	s_addc_u32 s27, s40, s27
	s_and_b64 s[30:31], s[4:5], exec
	s_cselect_b32 s11, s27, s29
	s_cselect_b32 s21, s26, s28
	s_add_u32 s8, s8, 0x40080
	s_addc_u32 s9, s9, 0
	s_mov_b32 s100, 0x40000
	s_mov_b32 s101, 0
	s_add_u32 s23, s28, 0x100
	s_addc_u32 s44, s29, 0
	s_mov_b32 s45, -2
	s_add_u32 s28, s8, 0xfffc0080
	s_addc_u32 s29, s9, -1
	s_cmp_eq_u32 s45, 12
	s_cselect_b32 s31, s3, s29
	s_cselect_b32 s30, s7, s28
	s_cselect_b32 s29, s11, s44
	s_cselect_b32 s28, s21, s23
	ds_read_b128 v[132:135], v204
	ds_read_b128 v[136:139], v204 offset:1024
	ds_read_b128 v[140:143], v204 offset:2048
	ds_read_b128 v[144:147], v204 offset:3072
	ds_read_b128 v[148:151], v204 offset:16384
	ds_read_b128 v[152:155], v204 offset:17408
	ds_read_b128 v[156:159], v204 offset:18432
	ds_read_b128 v[160:163], v204 offset:19456
	v_lshl_add_u64 v[194:195], s[8:9], 0, v[178:179]
	s_add_i32 m0, s42, 0xc000
	ds_read_b128 v[164:167], v205
	ds_read_b128 v[182:185], v205 offset:1024
	ds_read_b128 v[186:189], v205 offset:2048
	ds_read_b128 v[190:193], v205 offset:3072
	ds_read_b128 v[208:211], v205 offset:4096
	ds_read_b128 v[212:215], v205 offset:5120
	ds_read_b128 v[216:219], v205 offset:6144
	ds_read_b128 v[220:223], v205 offset:7168
	global_load_lds_dwordx4 v[194:195], off
	s_add_i32 m0, s42, 0xe000
	v_lshl_add_u64 v[194:195], s[8:9], 0, v[180:181]
	global_load_lds_dwordx4 v[194:195], off
	s_waitcnt vmcnt(8) lgkmcnt(0)
	s_barrier
	s_setprio 1
	v_mfma_f32_16x16x32_bf16 v[128:131], v[132:135], v[164:167], 0
	v_mfma_f32_16x16x32_bf16 v[124:127], v[140:143], v[164:167], 0
	v_mfma_f32_16x16x32_bf16 v[112:115], v[132:135], v[186:189], 0
	v_mfma_f32_16x16x32_bf16 v[108:111], v[140:143], v[186:189], 0
	v_mfma_f32_16x16x32_bf16 v[96:99], v[132:135], v[208:211], 0
	v_mfma_f32_16x16x32_bf16 v[92:95], v[140:143], v[208:211], 0
	v_mfma_f32_16x16x32_bf16 v[80:83], v[132:135], v[216:219], 0
	v_mfma_f32_16x16x32_bf16 v[76:79], v[140:143], v[216:219], 0
	v_mfma_f32_16x16x32_bf16 v[128:131], v[136:139], v[182:185], v[128:131]
	v_mfma_f32_16x16x32_bf16 v[124:127], v[144:147], v[182:185], v[124:127]
	v_mfma_f32_16x16x32_bf16 v[112:115], v[136:139], v[190:193], v[112:115]
	v_mfma_f32_16x16x32_bf16 v[108:111], v[144:147], v[190:193], v[108:111]
	v_mfma_f32_16x16x32_bf16 v[96:99], v[136:139], v[212:215], v[96:99]
	v_mfma_f32_16x16x32_bf16 v[92:95], v[144:147], v[212:215], v[92:95]
	v_mfma_f32_16x16x32_bf16 v[80:83], v[136:139], v[220:223], v[80:83]
	v_mfma_f32_16x16x32_bf16 v[76:79], v[144:147], v[220:223], v[76:79]
	s_setprio 0
	s_setprio 1
	v_mfma_f32_16x16x32_bf16 v[120:123], v[148:151], v[164:167], 0
	v_mfma_f32_16x16x32_bf16 v[116:119], v[156:159], v[164:167], 0
	v_mfma_f32_16x16x32_bf16 v[104:107], v[148:151], v[186:189], 0
	v_mfma_f32_16x16x32_bf16 v[100:103], v[156:159], v[186:189], 0
	v_mfma_f32_16x16x32_bf16 v[88:91], v[148:151], v[208:211], 0
	v_mfma_f32_16x16x32_bf16 v[84:87], v[156:159], v[208:211], 0
	v_mfma_f32_16x16x32_bf16 v[72:75], v[148:151], v[216:219], 0
	v_mfma_f32_16x16x32_bf16 v[68:71], v[156:159], v[216:219], 0
	v_mfma_f32_16x16x32_bf16 v[120:123], v[152:155], v[182:185], v[120:123]
	v_mfma_f32_16x16x32_bf16 v[116:119], v[160:163], v[182:185], v[116:119]
	v_mfma_f32_16x16x32_bf16 v[104:107], v[152:155], v[190:193], v[104:107]
	v_mfma_f32_16x16x32_bf16 v[100:103], v[160:163], v[190:193], v[100:103]
	v_mfma_f32_16x16x32_bf16 v[88:91], v[152:155], v[212:215], v[88:91]
	v_mfma_f32_16x16x32_bf16 v[84:87], v[160:163], v[212:215], v[84:87]
	v_mfma_f32_16x16x32_bf16 v[72:75], v[152:155], v[220:223], v[72:75]
	v_mfma_f32_16x16x32_bf16 v[68:71], v[160:163], v[220:223], v[68:71]
	s_setprio 0
	s_barrier
	v_lshl_add_u64 v[194:195], s[28:29], 0, v[168:169]
	s_add_i32 m0, s41, 0x10000
	ds_read_b128 v[164:167], v205 offset:16384
	ds_read_b128 v[182:185], v205 offset:17408
	ds_read_b128 v[186:189], v205 offset:18432
	ds_read_b128 v[190:193], v205 offset:19456
	ds_read_b128 v[208:211], v205 offset:20480
	ds_read_b128 v[212:215], v205 offset:21504
	ds_read_b128 v[216:219], v205 offset:22528
	ds_read_b128 v[220:223], v205 offset:23552
	global_load_lds_dwordx4 v[194:195], off
	s_add_i32 m0, s41, 0x12000
	v_lshl_add_u64 v[202:203], s[28:29], 0, v[172:173]
	global_load_lds_dwordx4 v[202:203], off
	v_lshl_add_u64 v[224:225], v[194:195], 0, s[100:101]
	s_add_i32 m0, s41, 0x14000
	v_lshl_add_u64 v[226:227], s[30:31], 0, v[170:171]
	global_load_lds_dwordx4 v[224:225], off
	s_add_i32 m0, s41, 0x16000
	v_lshl_add_u64 v[224:225], v[202:203], 0, s[100:101]
	global_load_lds_dwordx4 v[224:225], off
	s_mov_b32 m0, s42
	v_lshl_add_u64 v[224:225], s[30:31], 0, v[0:1]
	global_load_lds_dwordx4 v[224:225], off
	s_mov_b32 m0, s43
	s_add_i32 s53, 0, 0x18000
	global_load_lds_dwordx4 v[226:227], off
	s_waitcnt vmcnt(8) lgkmcnt(0)
	s_barrier
; #define PG8_STAGE(bufoff, gbase, voff) do { _Pragma("unroll") for (int _i = 0; _i < 2; ++_i) \
;         __builtin_amdgcn_global_load_lds((const unsigned*)((const char*)(gbase) + (voff)[_i]), (PG8_LAS unsigned*)(lds + (bufoff) + ldsw + _i * 8192), 16, 0, 0); } while (0)
; #define PG8_LDA(dst, b, h) do { _Pragma("unroll") for (int m = 0; m < 4; ++m) _Pragma("unroll") for (int k = 0; k < 2; ++k) dst[m][k] = *(const PG8_LAS bf16x8*)(lds + PG8_SA(b, h) + aoff + m * 2048 + k * 1024); } while (0)
; #define PG8_LDB(dst, b, h) do { _Pragma("unroll") for (int n = 0; n < 2; ++n) _Pragma("unroll") for (int k = 0; k < 2; ++k) dst[n][k] = *(const PG8_LAS bf16x8*)(lds + PG8_SB(b, h) + boff + n * 2048 + k * 1024); } while (0)
; #define PG8_MMA(ai, bj, At, Bt) do { __builtin_amdgcn_s_setprio(1); _Pragma("unroll") for (int m = 0; m < 4; ++m) _Pragma("unroll") for (int n = 0; n < 2; ++n) _Pragma("unroll") for (int k = 0; k < 2; ++k) \
;         acc[ai][bj][m][n] = __builtin_amdgcn_mfma_f32_16x16x32_bf16(Bt[n][k], At[m][k], acc[ai][bj][m][n], 0, 0, 0); __builtin_amdgcn_s_setprio(0); } while (0)
; #define PG8_WAIT_V(n) asm volatile("s_waitcnt vmcnt(" #n ")" ::: "memory")
; #define PG8_WAIT_L(n) asm volatile("s_waitcnt lgkmcnt(" #n ")" ::: "memory")
; #define PG8_BAR __builtin_amdgcn_s_barrier()
; #define PG8_SCHED __builtin_amdgcn_sched_barrier(0)
; template <class Epi, class Sched, bool ALIGN_EPI = false, bool SP2 = false>
; __device__ __forceinline__ void gemm_phase(PG8_LAS unsigned char* lds, const Gemm g, const Sched& S, const Epi& E) {
;     ...
;             PG8_LDB(B0, 0, 0); PG8_LDB(B1, 0, 1); PG8_SCHED; PG8_LDA(At, 0, 0); PG8_STAGE(PG8_SA(1, 1), a1 + hstep, voffA);
;             PG8_WAIT_V(8); PG8_WAIT_L(0); PG8_BAR; PG8_MMA(0, 0, At, B0); PG8_MMA(0, 1, At, B1); PG8_BAR; PG8_SCHED;
;             PG8_LDA(At, 0, 1); PG8_STAGE(PG8_SB(0, 0), b2, voffB); PG8_STAGE(PG8_SB(0, 1), b2 + hstep, voffB); PG8_STAGE(PG8_SA(0, 0), a2, voffA);
;             PG8_WAIT_V(8); PG8_WAIT_L(0); PG8_BAR; PG8_MMA(1, 0, At, B0); PG8_MMA(1, 1, At, B1); PG8_BAR; PG8_SCHED;
	s_setprio 1
	v_mfma_f32_16x16x32_bf16 v[64:67], v[132:135], v[164:167], 0
	v_mfma_f32_16x16x32_bf16 v[60:63], v[140:143], v[164:167], 0
	v_mfma_f32_16x16x32_bf16 v[48:51], v[132:135], v[186:189], 0
	v_mfma_f32_16x16x32_bf16 v[44:47], v[140:143], v[186:189], 0
	v_mfma_f32_16x16x32_bf16 v[32:35], v[132:135], v[208:211], 0
	v_mfma_f32_16x16x32_bf16 v[28:31], v[140:143], v[208:211], 0
	v_mfma_f32_16x16x32_bf16 v[16:19], v[132:135], v[216:219], 0
	v_mfma_f32_16x16x32_bf16 v[12:15], v[140:143], v[216:219], 0
	v_mfma_f32_16x16x32_bf16 v[64:67], v[136:139], v[182:185], v[64:67]
	v_mfma_f32_16x16x32_bf16 v[60:63], v[144:147], v[182:185], v[60:63]
	v_mfma_f32_16x16x32_bf16 v[48:51], v[136:139], v[190:193], v[48:51]
	v_mfma_f32_16x16x32_bf16 v[44:47], v[144:147], v[190:193], v[44:47]
	v_mfma_f32_16x16x32_bf16 v[32:35], v[136:139], v[212:215], v[32:35]
	v_mfma_f32_16x16x32_bf16 v[28:31], v[144:147], v[212:215], v[28:31]
	v_mfma_f32_16x16x32_bf16 v[16:19], v[136:139], v[220:223], v[16:19]
	v_mfma_f32_16x16x32_bf16 v[12:15], v[144:147], v[220:223], v[12:15]
	s_setprio 0
	s_setprio 1
	v_mfma_f32_16x16x32_bf16 v[56:59], v[148:151], v[164:167], 0
	v_mfma_f32_16x16x32_bf16 v[52:55], v[156:159], v[164:167], 0
	v_mfma_f32_16x16x32_bf16 v[40:43], v[148:151], v[186:189], 0
	v_mfma_f32_16x16x32_bf16 v[36:39], v[156:159], v[186:189], 0
	v_mfma_f32_16x16x32_bf16 v[24:27], v[148:151], v[208:211], 0
	v_mfma_f32_16x16x32_bf16 v[20:23], v[156:159], v[208:211], 0
	v_mfma_f32_16x16x32_bf16 v[8:11], v[148:151], v[216:219], 0
	v_mfma_f32_16x16x32_bf16 v[4:7], v[156:159], v[216:219], 0
	v_mfma_f32_16x16x32_bf16 v[56:59], v[152:155], v[182:185], v[56:59]
	v_mfma_f32_16x16x32_bf16 v[52:55], v[160:163], v[182:185], v[52:55]
	v_mfma_f32_16x16x32_bf16 v[40:43], v[152:155], v[190:193], v[40:43]
	v_mfma_f32_16x16x32_bf16 v[36:39], v[160:163], v[190:193], v[36:39]
	v_mfma_f32_16x16x32_bf16 v[24:27], v[152:155], v[212:215], v[24:27]
	v_mfma_f32_16x16x32_bf16 v[20:23], v[160:163], v[212:215], v[20:23]
	v_mfma_f32_16x16x32_bf16 v[8:11], v[152:155], v[220:223], v[8:11]
	v_mfma_f32_16x16x32_bf16 v[4:7], v[160:163], v[220:223], v[4:7]
	s_setprio 0
	s_barrier
	s_branch .Lkmid_0
.LBB0_100:
	s_add_u32 s28, s8, 0xfffc0080
	s_addc_u32 s29, s9, -1
	s_cmp_eq_u32 s45, 12
	s_cselect_b32 s31, s3, s29
	s_cselect_b32 s30, s7, s28
	s_cselect_b32 s29, s11, s44
	s_cselect_b32 s28, s21, s23
	ds_read_b128 v[132:135], v204
	ds_read_b128 v[136:139], v204 offset:1024
	ds_read_b128 v[140:143], v204 offset:2048
	ds_read_b128 v[144:147], v204 offset:3072
	ds_read_b128 v[148:151], v204 offset:16384
	ds_read_b128 v[152:155], v204 offset:17408
	ds_read_b128 v[156:159], v204 offset:18432
	ds_read_b128 v[160:163], v204 offset:19456
	v_lshl_add_u64 v[194:195], s[8:9], 0, v[178:179]
	s_add_i32 m0, s42, 0xc000
	ds_read_b128 v[164:167], v205
	ds_read_b128 v[182:185], v205 offset:1024
	ds_read_b128 v[186:189], v205 offset:2048
	ds_read_b128 v[190:193], v205 offset:3072
	ds_read_b128 v[208:211], v205 offset:4096
	ds_read_b128 v[212:215], v205 offset:5120
	ds_read_b128 v[216:219], v205 offset:6144
	ds_read_b128 v[220:223], v205 offset:7168
	global_load_lds_dwordx4 v[194:195], off
	s_add_i32 m0, s42, 0xe000
	v_lshl_add_u64 v[194:195], s[8:9], 0, v[180:181]
	global_load_lds_dwordx4 v[194:195], off
	s_waitcnt vmcnt(8) lgkmcnt(0)
	s_barrier
	s_setprio 1
	v_mfma_f32_16x16x32_bf16 v[128:131], v[132:135], v[164:167], v[128:131]
	v_mfma_f32_16x16x32_bf16 v[124:127], v[140:143], v[164:167], v[124:127]
	v_mfma_f32_16x16x32_bf16 v[112:115], v[132:135], v[186:189], v[112:115]
	v_mfma_f32_16x16x32_bf16 v[108:111], v[140:143], v[186:189], v[108:111]
	v_mfma_f32_16x16x32_bf16 v[96:99], v[132:135], v[208:211], v[96:99]
	v_mfma_f32_16x16x32_bf16 v[92:95], v[140:143], v[208:211], v[92:95]
	v_mfma_f32_16x16x32_bf16 v[80:83], v[132:135], v[216:219], v[80:83]
	v_mfma_f32_16x16x32_bf16 v[76:79], v[140:143], v[216:219], v[76:79]
	v_mfma_f32_16x16x32_bf16 v[128:131], v[136:139], v[182:185], v[128:131]
	v_mfma_f32_16x16x32_bf16 v[124:127], v[144:147], v[182:185], v[124:127]
	v_mfma_f32_16x16x32_bf16 v[112:115], v[136:139], v[190:193], v[112:115]
	v_mfma_f32_16x16x32_bf16 v[108:111], v[144:147], v[190:193], v[108:111]
	v_mfma_f32_16x16x32_bf16 v[96:99], v[136:139], v[212:215], v[96:99]
	v_mfma_f32_16x16x32_bf16 v[92:95], v[144:147], v[212:215], v[92:95]
	v_mfma_f32_16x16x32_bf16 v[80:83], v[136:139], v[220:223], v[80:83]
	v_mfma_f32_16x16x32_bf16 v[76:79], v[144:147], v[220:223], v[76:79]
	s_setprio 0
	s_setprio 1
	v_mfma_f32_16x16x32_bf16 v[120:123], v[148:151], v[164:167], v[120:123]
	v_mfma_f32_16x16x32_bf16 v[116:119], v[156:159], v[164:167], v[116:119]
	v_mfma_f32_16x16x32_bf16 v[104:107], v[148:151], v[186:189], v[104:107]
	v_mfma_f32_16x16x32_bf16 v[100:103], v[156:159], v[186:189], v[100:103]
	v_mfma_f32_16x16x32_bf16 v[88:91], v[148:151], v[208:211], v[88:91]
	v_mfma_f32_16x16x32_bf16 v[84:87], v[156:159], v[208:211], v[84:87]
	v_mfma_f32_16x16x32_bf16 v[72:75], v[148:151], v[216:219], v[72:75]
	v_mfma_f32_16x16x32_bf16 v[68:71], v[156:159], v[216:219], v[68:71]
	v_mfma_f32_16x16x32_bf16 v[120:123], v[152:155], v[182:185], v[120:123]
	v_mfma_f32_16x16x32_bf16 v[116:119], v[160:163], v[182:185], v[116:119]
	v_mfma_f32_16x16x32_bf16 v[104:107], v[152:155], v[190:193], v[104:107]
	v_mfma_f32_16x16x32_bf16 v[100:103], v[160:163], v[190:193], v[100:103]
	v_mfma_f32_16x16x32_bf16 v[88:91], v[152:155], v[212:215], v[88:91]
	v_mfma_f32_16x16x32_bf16 v[84:87], v[160:163], v[212:215], v[84:87]
	v_mfma_f32_16x16x32_bf16 v[72:75], v[152:155], v[220:223], v[72:75]
	v_mfma_f32_16x16x32_bf16 v[68:71], v[160:163], v[220:223], v[68:71]
	s_setprio 0
	s_barrier
; #define PG8_STAGE(bufoff, gbase, voff) do { _Pragma("unroll") for (int _i = 0; _i < 2; ++_i) \
;         __builtin_amdgcn_global_load_lds((const unsigned*)((const char*)(gbase) + (voff)[_i]), (PG8_LAS unsigned*)(lds + (bufoff) + ldsw + _i * 8192), 16, 0, 0); } while (0)
; #define PG8_LDA(dst, b, h) do { _Pragma("unroll") for (int m = 0; m < 4; ++m) _Pragma("unroll") for (int k = 0; k < 2; ++k) dst[m][k] = *(const PG8_LAS bf16x8*)(lds + PG8_SA(b, h) + aoff + m * 2048 + k * 1024); } while (0)
; #define PG8_MMA(ai, bj, At, Bt) do { __builtin_amdgcn_s_setprio(1); _Pragma("unroll") for (int m = 0; m < 4; ++m) _Pragma("unroll") for (int n = 0; n < 2; ++n) _Pragma("unroll") for (int k = 0; k < 2; ++k) \
;         acc[ai][bj][m][n] = __builtin_amdgcn_mfma_f32_16x16x32_bf16(Bt[n][k], At[m][k], acc[ai][bj][m][n], 0, 0, 0); __builtin_amdgcn_s_setprio(0); } while (0)
; #define PG8_WAIT_V(n) asm volatile("s_waitcnt vmcnt(" #n ")" ::: "memory")
; #define PG8_WAIT_L(n) asm volatile("s_waitcnt lgkmcnt(" #n ")" ::: "memory")
; #define PG8_BAR __builtin_amdgcn_s_barrier()
; #define PG8_SCHED __builtin_amdgcn_sched_barrier(0)
; template <class Epi, class Sched, bool ALIGN_EPI = false, bool SP2 = false>
; __device__ __forceinline__ void gemm_phase(PG8_LAS unsigned char* lds, const Gemm g, const Sched& S, const Epi& E) {
;     ...
;             PG8_LDA(At, 0, 1); PG8_STAGE(PG8_SB(0, 0), b2, voffB); PG8_STAGE(PG8_SB(0, 1), b2 + hstep, voffB); PG8_STAGE(PG8_SA(0, 0), a2, voffA);
;             PG8_WAIT_V(8); PG8_WAIT_L(0); PG8_BAR; PG8_MMA(1, 0, At, B0); PG8_MMA(1, 1, At, B1); PG8_BAR; PG8_SCHED;
	v_lshl_add_u64 v[194:195], s[28:29], 0, v[168:169]
	s_add_i32 m0, s41, 0x10000
	ds_read_b128 v[164:167], v205 offset:16384
	ds_read_b128 v[182:185], v205 offset:17408
	ds_read_b128 v[186:189], v205 offset:18432
	ds_read_b128 v[190:193], v205 offset:19456
	ds_read_b128 v[208:211], v205 offset:20480
	ds_read_b128 v[212:215], v205 offset:21504
	ds_read_b128 v[216:219], v205 offset:22528
	ds_read_b128 v[220:223], v205 offset:23552
	global_load_lds_dwordx4 v[194:195], off
	s_add_i32 m0, s41, 0x12000
	v_lshl_add_u64 v[202:203], s[28:29], 0, v[172:173]
	global_load_lds_dwordx4 v[202:203], off
	v_lshl_add_u64 v[224:225], v[194:195], 0, s[100:101]
	s_add_i32 m0, s41, 0x14000
	v_lshl_add_u64 v[226:227], s[30:31], 0, v[170:171]
	global_load_lds_dwordx4 v[224:225], off
	s_add_i32 m0, s41, 0x16000
	v_lshl_add_u64 v[224:225], v[202:203], 0, s[100:101]
	global_load_lds_dwordx4 v[224:225], off
	s_mov_b32 m0, s42
	v_lshl_add_u64 v[224:225], s[30:31], 0, v[0:1]
	global_load_lds_dwordx4 v[224:225], off
	s_mov_b32 m0, s43
	s_add_i32 s53, 0, 0x18000
	global_load_lds_dwordx4 v[226:227], off
	s_waitcnt vmcnt(8) lgkmcnt(0)
	s_barrier
	s_setprio 1
	v_mfma_f32_16x16x32_bf16 v[64:67], v[132:135], v[164:167], v[64:67]
	v_mfma_f32_16x16x32_bf16 v[60:63], v[140:143], v[164:167], v[60:63]
	v_mfma_f32_16x16x32_bf16 v[48:51], v[132:135], v[186:189], v[48:51]
	v_mfma_f32_16x16x32_bf16 v[44:47], v[140:143], v[186:189], v[44:47]
	v_mfma_f32_16x16x32_bf16 v[32:35], v[132:135], v[208:211], v[32:35]
	v_mfma_f32_16x16x32_bf16 v[28:31], v[140:143], v[208:211], v[28:31]
	v_mfma_f32_16x16x32_bf16 v[16:19], v[132:135], v[216:219], v[16:19]
	v_mfma_f32_16x16x32_bf16 v[12:15], v[140:143], v[216:219], v[12:15]
	v_mfma_f32_16x16x32_bf16 v[64:67], v[136:139], v[182:185], v[64:67]
	v_mfma_f32_16x16x32_bf16 v[60:63], v[144:147], v[182:185], v[60:63]
	v_mfma_f32_16x16x32_bf16 v[48:51], v[136:139], v[190:193], v[48:51]
	v_mfma_f32_16x16x32_bf16 v[44:47], v[144:147], v[190:193], v[44:47]
	v_mfma_f32_16x16x32_bf16 v[32:35], v[136:139], v[212:215], v[32:35]
	v_mfma_f32_16x16x32_bf16 v[28:31], v[144:147], v[212:215], v[28:31]
	v_mfma_f32_16x16x32_bf16 v[16:19], v[136:139], v[220:223], v[16:19]
	v_mfma_f32_16x16x32_bf16 v[12:15], v[144:147], v[220:223], v[12:15]
	s_setprio 0
	s_setprio 1
	v_mfma_f32_16x16x32_bf16 v[56:59], v[148:151], v[164:167], v[56:59]
	v_mfma_f32_16x16x32_bf16 v[52:55], v[156:159], v[164:167], v[52:55]
	v_mfma_f32_16x16x32_bf16 v[40:43], v[148:151], v[186:189], v[40:43]
	v_mfma_f32_16x16x32_bf16 v[36:39], v[156:159], v[186:189], v[36:39]
	v_mfma_f32_16x16x32_bf16 v[24:27], v[148:151], v[208:211], v[24:27]
	v_mfma_f32_16x16x32_bf16 v[20:23], v[156:159], v[208:211], v[20:23]
	v_mfma_f32_16x16x32_bf16 v[8:11], v[148:151], v[216:219], v[8:11]
	v_mfma_f32_16x16x32_bf16 v[4:7], v[156:159], v[216:219], v[4:7]
	v_mfma_f32_16x16x32_bf16 v[56:59], v[152:155], v[182:185], v[56:59]
	v_mfma_f32_16x16x32_bf16 v[52:55], v[160:163], v[182:185], v[52:55]
	v_mfma_f32_16x16x32_bf16 v[40:43], v[152:155], v[190:193], v[40:43]
	v_mfma_f32_16x16x32_bf16 v[36:39], v[160:163], v[190:193], v[36:39]
	v_mfma_f32_16x16x32_bf16 v[24:27], v[152:155], v[212:215], v[24:27]
	v_mfma_f32_16x16x32_bf16 v[20:23], v[160:163], v[212:215], v[20:23]
	v_mfma_f32_16x16x32_bf16 v[8:11], v[152:155], v[220:223], v[8:11]
	v_mfma_f32_16x16x32_bf16 v[4:7], v[160:163], v[220:223], v[4:7]
	s_setprio 0
	s_barrier
; #define PG8_STAGE(bufoff, gbase, voff) do { _Pragma("unroll") for (int _i = 0; _i < 2; ++_i) \
;         __builtin_amdgcn_global_load_lds((const unsigned*)((const char*)(gbase) + (voff)[_i]), (PG8_LAS unsigned*)(lds + (bufoff) + ldsw + _i * 8192), 16, 0, 0); } while (0)
; #define PG8_LDA(dst, b, h) do { _Pragma("unroll") for (int m = 0; m < 4; ++m) _Pragma("unroll") for (int k = 0; k < 2; ++k) dst[m][k] = *(const PG8_LAS bf16x8*)(lds + PG8_SA(b, h) + aoff + m * 2048 + k * 1024); } while (0)
; #define PG8_LDB(dst, b, h) do { _Pragma("unroll") for (int n = 0; n < 2; ++n) _Pragma("unroll") for (int k = 0; k < 2; ++k) dst[n][k] = *(const PG8_LAS bf16x8*)(lds + PG8_SB(b, h) + boff + n * 2048 + k * 1024); } while (0)
; template <class Epi, class Sched, bool ALIGN_EPI = false, bool SP2 = false>
; __device__ __forceinline__ void gemm_phase(PG8_LAS unsigned char* lds, const Gemm g, const Sched& S, const Epi& E) {
;     ...
;         for (int t = 0; t < nt; t += 2) {
;             const bool last = (t == nt - 2);
;             const char* a1 = cA + (size_t)(t + 1) * kstep;
;             const char* a2 = last ? nA : cA + (size_t)(t + 2) * kstep; const char* b2 = last ? nB : cB + (size_t)(t + 2) * kstep;
;             const char* a3 = a2 + kstep; const char* b3 = b2 + kstep;
;             if (last && has_next) S.a_ready(nxt);
;             if constexpr (SP2) {
;             PG8_LDB(B0, 0, 0); PG8_LDB(B1, 0, 1); PG8_SCHED; PG8_LDA(At, 0, 0); PG8_STAGE(PG8_SA(1, 1), a1 + hstep, voffA);
;             PG8_WAIT_V(8); PG8_WAIT_L(0); PG8_BAR; PG8_MMA(0, 0, At, B0); PG8_MMA(0, 1, At, B1); PG8_BAR; PG8_SCHED;
;             PG8_LDA(At, 0, 1); PG8_STAGE(PG8_SB(0, 0), b2, voffB); PG8_STAGE(PG8_SB(0, 1), b2 + hstep, voffB); PG8_STAGE(PG8_SA(0, 0), a2, voffA);
;             PG8_WAIT_V(8); PG8_WAIT_L(0); PG8_BAR; PG8_MMA(1, 0, At, B0); PG8_MMA(1, 1, At, B1); PG8_BAR; PG8_SCHED;
;             PG8_LDB(B0, 1, 0); PG8_LDB(B1, 1, 1); PG8_SCHED; PG8_LDA(At, 1, 0); PG8_STAGE(PG8_SA(0, 1), a2 + hstep, voffA);
;             PG8_WAIT_V(8); PG8_WAIT_L(0); PG8_BAR; PG8_MMA(0, 0, At, B0); PG8_MMA(0, 1, At, B1); PG8_BAR; PG8_SCHED;
;             PG8_LDA(At, 1, 1); PG8_STAGE(PG8_SB(1, 0), b3, voffB); PG8_STAGE(PG8_SB(1, 1), b3 + hstep, voffB); PG8_STAGE(PG8_SA(1, 0), a3, voffA);
;             PG8_WAIT_V(8); PG8_WAIT_L(0); PG8_BAR; PG8_MMA(1, 0, At, B0); PG8_MMA(1, 1, At, B1); PG8_BAR; PG8_SCHED;
.Lkmid_0:
	ds_read_b128 v[132:135], v204 offset:32768
	ds_read_b128 v[136:139], v204 offset:33792
	ds_read_b128 v[140:143], v204 offset:34816
	ds_read_b128 v[144:147], v204 offset:35840
	ds_read_b128 v[148:151], v204 offset:49152
	ds_read_b128 v[152:155], v204 offset:50176
	ds_read_b128 v[156:159], v204 offset:51200
	ds_read_b128 v[160:163], v204 offset:52224
	s_mov_b32 m0, s46
	v_lshl_add_u64 v[228:229], v[224:225], 0, s[100:101]
	ds_read_b128 v[164:167], v205 offset:32768
	ds_read_b128 v[182:185], v205 offset:33792
	ds_read_b128 v[186:189], v205 offset:34816
	ds_read_b128 v[190:193], v205 offset:35840
	ds_read_b128 v[208:211], v205 offset:36864
	ds_read_b128 v[212:215], v205 offset:37888
	ds_read_b128 v[216:219], v205 offset:38912
	ds_read_b128 v[220:223], v205 offset:39936
	global_load_lds_dwordx4 v[228:229], off
	s_mov_b32 m0, s47
	v_lshl_add_u64 v[228:229], v[226:227], 0, s[100:101]
	global_load_lds_dwordx4 v[228:229], off
	s_waitcnt vmcnt(8) lgkmcnt(0)
	s_barrier
	s_setprio 1
	v_mfma_f32_16x16x32_bf16 v[128:131], v[132:135], v[164:167], v[128:131]
	v_mfma_f32_16x16x32_bf16 v[124:127], v[140:143], v[164:167], v[124:127]
	v_mfma_f32_16x16x32_bf16 v[112:115], v[132:135], v[186:189], v[112:115]
	v_mfma_f32_16x16x32_bf16 v[108:111], v[140:143], v[186:189], v[108:111]
	v_mfma_f32_16x16x32_bf16 v[96:99], v[132:135], v[208:211], v[96:99]
	v_mfma_f32_16x16x32_bf16 v[92:95], v[140:143], v[208:211], v[92:95]
	v_mfma_f32_16x16x32_bf16 v[80:83], v[132:135], v[216:219], v[80:83]
	v_mfma_f32_16x16x32_bf16 v[76:79], v[140:143], v[216:219], v[76:79]
	v_mfma_f32_16x16x32_bf16 v[128:131], v[136:139], v[182:185], v[128:131]
	v_mfma_f32_16x16x32_bf16 v[124:127], v[144:147], v[182:185], v[124:127]
	v_mfma_f32_16x16x32_bf16 v[112:115], v[136:139], v[190:193], v[112:115]
	v_mfma_f32_16x16x32_bf16 v[108:111], v[144:147], v[190:193], v[108:111]
	v_mfma_f32_16x16x32_bf16 v[96:99], v[136:139], v[212:215], v[96:99]
	v_mfma_f32_16x16x32_bf16 v[92:95], v[144:147], v[212:215], v[92:95]
	v_mfma_f32_16x16x32_bf16 v[80:83], v[136:139], v[220:223], v[80:83]
	v_mfma_f32_16x16x32_bf16 v[76:79], v[144:147], v[220:223], v[76:79]
	s_setprio 0
	s_setprio 1
	v_mfma_f32_16x16x32_bf16 v[120:123], v[148:151], v[164:167], v[120:123]
	v_mfma_f32_16x16x32_bf16 v[116:119], v[156:159], v[164:167], v[116:119]
	v_mfma_f32_16x16x32_bf16 v[104:107], v[148:151], v[186:189], v[104:107]
	v_mfma_f32_16x16x32_bf16 v[100:103], v[156:159], v[186:189], v[100:103]
	v_mfma_f32_16x16x32_bf16 v[88:91], v[148:151], v[208:211], v[88:91]
	v_mfma_f32_16x16x32_bf16 v[84:87], v[156:159], v[208:211], v[84:87]
	v_mfma_f32_16x16x32_bf16 v[72:75], v[148:151], v[216:219], v[72:75]
	v_mfma_f32_16x16x32_bf16 v[68:71], v[156:159], v[216:219], v[68:71]
	v_mfma_f32_16x16x32_bf16 v[120:123], v[152:155], v[182:185], v[120:123]
	v_mfma_f32_16x16x32_bf16 v[116:119], v[160:163], v[182:185], v[116:119]
	v_mfma_f32_16x16x32_bf16 v[104:107], v[152:155], v[190:193], v[104:107]
	v_mfma_f32_16x16x32_bf16 v[100:103], v[160:163], v[190:193], v[100:103]
	v_mfma_f32_16x16x32_bf16 v[88:91], v[152:155], v[212:215], v[88:91]
	v_mfma_f32_16x16x32_bf16 v[84:87], v[160:163], v[212:215], v[84:87]
	v_mfma_f32_16x16x32_bf16 v[72:75], v[152:155], v[220:223], v[72:75]
	v_mfma_f32_16x16x32_bf16 v[68:71], v[160:163], v[220:223], v[68:71]
	s_setprio 0
	s_barrier
	s_add_i32 m0, s41, 0x17f80
	ds_read_b128 v[164:167], v205 offset:49152
	ds_read_b128 v[182:185], v205 offset:50176
	ds_read_b128 v[186:189], v205 offset:51200
	ds_read_b128 v[190:193], v205 offset:52224
	ds_read_b128 v[208:211], v205 offset:53248
	ds_read_b128 v[212:215], v205 offset:54272
	ds_read_b128 v[216:219], v205 offset:55296
	ds_read_b128 v[220:223], v205 offset:56320
	global_load_lds_dwordx4 v[194:195], off offset:128
	s_add_i32 m0, s41, 0x19f80
	v_lshl_add_u64 v[194:195], v[194:195], 0, s[100:101]
	global_load_lds_dwordx4 v[202:203], off offset:128
	s_add_i32 m0, s41, 0x1bf80
	v_lshl_add_u64 v[228:229], v[202:203], 0, s[100:101]
	global_load_lds_dwordx4 v[194:195], off offset:128
	s_add_i32 m0, s41, 0x1df80
	s_add_i32 s45, s45, 2
	global_load_lds_dwordx4 v[228:229], off offset:128
	s_add_i32 m0, s50, 0xffffff80
	s_add_u32 s8, s8, 0x100
	s_addc_u32 s9, s9, 0
	global_load_lds_dwordx4 v[224:225], off offset:128
	s_add_i32 m0, s51, 0xffffff80
	s_add_u32 s23, s23, 0x100
	s_addc_u32 s44, s44, 0
	global_load_lds_dwordx4 v[226:227], off offset:128
	s_waitcnt vmcnt(8) lgkmcnt(0)
	s_barrier
	s_setprio 1
	v_mfma_f32_16x16x32_bf16 v[64:67], v[132:135], v[164:167], v[64:67]
	v_mfma_f32_16x16x32_bf16 v[60:63], v[140:143], v[164:167], v[60:63]
	v_mfma_f32_16x16x32_bf16 v[48:51], v[132:135], v[186:189], v[48:51]
	v_mfma_f32_16x16x32_bf16 v[44:47], v[140:143], v[186:189], v[44:47]
	v_mfma_f32_16x16x32_bf16 v[32:35], v[132:135], v[208:211], v[32:35]
	v_mfma_f32_16x16x32_bf16 v[28:31], v[140:143], v[208:211], v[28:31]
	v_mfma_f32_16x16x32_bf16 v[16:19], v[132:135], v[216:219], v[16:19]
	v_mfma_f32_16x16x32_bf16 v[12:15], v[140:143], v[216:219], v[12:15]
	v_mfma_f32_16x16x32_bf16 v[64:67], v[136:139], v[182:185], v[64:67]
	v_mfma_f32_16x16x32_bf16 v[60:63], v[144:147], v[182:185], v[60:63]
	v_mfma_f32_16x16x32_bf16 v[48:51], v[136:139], v[190:193], v[48:51]
	v_mfma_f32_16x16x32_bf16 v[44:47], v[144:147], v[190:193], v[44:47]
	v_mfma_f32_16x16x32_bf16 v[32:35], v[136:139], v[212:215], v[32:35]
	v_mfma_f32_16x16x32_bf16 v[28:31], v[144:147], v[212:215], v[28:31]
	v_mfma_f32_16x16x32_bf16 v[16:19], v[136:139], v[220:223], v[16:19]
	v_mfma_f32_16x16x32_bf16 v[12:15], v[144:147], v[220:223], v[12:15]
	s_setprio 0
	s_setprio 1
	v_mfma_f32_16x16x32_bf16 v[56:59], v[148:151], v[164:167], v[56:59]
	v_mfma_f32_16x16x32_bf16 v[52:55], v[156:159], v[164:167], v[52:55]
	v_mfma_f32_16x16x32_bf16 v[40:43], v[148:151], v[186:189], v[40:43]
	v_mfma_f32_16x16x32_bf16 v[36:39], v[156:159], v[186:189], v[36:39]
	v_mfma_f32_16x16x32_bf16 v[24:27], v[148:151], v[208:211], v[24:27]
	v_mfma_f32_16x16x32_bf16 v[20:23], v[156:159], v[208:211], v[20:23]
	v_mfma_f32_16x16x32_bf16 v[8:11], v[148:151], v[216:219], v[8:11]
	v_mfma_f32_16x16x32_bf16 v[4:7], v[156:159], v[216:219], v[4:7]
	v_mfma_f32_16x16x32_bf16 v[56:59], v[152:155], v[182:185], v[56:59]
	v_mfma_f32_16x16x32_bf16 v[52:55], v[160:163], v[182:185], v[52:55]
	v_mfma_f32_16x16x32_bf16 v[40:43], v[152:155], v[190:193], v[40:43]
	v_mfma_f32_16x16x32_bf16 v[36:39], v[160:163], v[190:193], v[36:39]
	v_mfma_f32_16x16x32_bf16 v[24:27], v[152:155], v[212:215], v[24:27]
	v_mfma_f32_16x16x32_bf16 v[20:23], v[160:163], v[212:215], v[20:23]
	v_mfma_f32_16x16x32_bf16 v[8:11], v[152:155], v[220:223], v[8:11]
	v_mfma_f32_16x16x32_bf16 v[4:7], v[160:163], v[220:223], v[4:7]
	s_setprio 0
	s_barrier
	s_cmp_gt_u32 s45, 13
	s_cbranch_scc0 .LBB0_100
	s_and_b64 vcc, exec, s[14:15]
	s_cbranch_vccz .LBB0_103
	s_barrier

; #define PG8_STAGE(bufoff, gbase, voff) do { _Pragma("unroll") for (int _i = 0; _i < 2; ++_i) \
;         __builtin_amdgcn_global_load_lds((const unsigned*)((const char*)(gbase) + (voff)[_i]), (PG8_LAS unsigned*)(lds + (bufoff) + ldsw + _i * 8192), 16, 0, 0); } while (0)
; #define PG8_LDA(dst, b, h) do { _Pragma("unroll") for (int m = 0; m < 4; ++m) _Pragma("unroll") for (int k = 0; k < 2; ++k) dst[m][k] = *(const PG8_LAS bf16x8*)(lds + PG8_SA(b, h) + aoff + m * 2048 + k * 1024); } while (0)
; #define PG8_LDB(dst, b, h) do { _Pragma("unroll") for (int n = 0; n < 2; ++n) _Pragma("unroll") for (int k = 0; k < 2; ++k) dst[n][k] = *(const PG8_LAS bf16x8*)(lds + PG8_SB(b, h) + boff + n * 2048 + k * 1024); } while (0)
; #define PG8_WAIT_V(n) asm volatile("s_waitcnt vmcnt(" #n ")" ::: "memory")
; #define PG8_WAIT_L(n) asm volatile("s_waitcnt lgkmcnt(" #n ")" ::: "memory")
; #define PG8_BAR __builtin_amdgcn_s_barrier()
; #define PG8_SCHED __builtin_amdgcn_sched_barrier(0)
; template <class Epi, class Sched, bool ALIGN_EPI = false, bool SP2 = false>
; __device__ __forceinline__ void gemm_phase(PG8_LAS unsigned char* lds, const Gemm g, const Sched& S, const Epi& E) {
;     ...
;         const bool has_next = S.next(ui + 1, nxt);
;         const char* nA = has_next ? (const char*)g.A + (size_t)nxt.pm * tstep : cA; const char* nB = has_next ? (const char*)g.Bt + (size_t)nxt.pn * tstep : cB;
;         for (int t = 0; t < nt; t += 2) {
;             const bool last = (t == nt - 2);
;             const char* a1 = cA + (size_t)(t + 1) * kstep;
;             const char* a2 = last ? nA : cA + (size_t)(t + 2) * kstep; const char* b2 = last ? nB : cB + (size_t)(t + 2) * kstep;
;             const char* a3 = a2 + kstep; const char* b3 = b2 + kstep;
;             if (last && has_next) S.a_ready(nxt);
;             if constexpr (SP2) {
;             PG8_LDB(B0, 0, 0); PG8_LDB(B1, 0, 1); PG8_SCHED; PG8_LDA(At, 0, 0); PG8_STAGE(PG8_SA(1, 1), a1 + hstep, voffA);
;             PG8_WAIT_V(8); PG8_WAIT_L(0); PG8_BAR; PG8_MMA(0, 0, At, B0); PG8_MMA(0, 1, At, B1); PG8_BAR; PG8_SCHED;
;             PG8_LDA(At, 0, 1); PG8_STAGE(PG8_SB(0, 0), b2, voffB); PG8_STAGE(PG8_SB(0, 1), b2 + hstep, voffB); PG8_STAGE(PG8_SA(0, 0), a2, voffA);
;             PG8_WAIT_V(8); PG8_WAIT_L(0); PG8_BAR; PG8_MMA(1, 0, At, B0); PG8_MMA(1, 1, At, B1); PG8_BAR; PG8_SCHED;
.LBB0_328:
	s_ashr_i32 s17, s16, 31
	s_lshl_b64 s[20:21], s[16:17], 19
	s_add_u32 s20, s37, s20
	s_addc_u32 s21, s38, s21
	s_and_b64 s[22:23], s[6:7], exec
	s_cselect_b32 s3, s21, s29
	s_cselect_b32 s17, s20, s28
	s_ashr_i32 s19, s18, 31
	s_lshl_b64 s[22:23], s[18:19], 19
	s_add_u32 s22, s39, s22
	s_addc_u32 s23, s40, s23
	s_and_b64 s[34:35], s[6:7], exec
	s_cselect_b32 s19, s23, s31
	s_cselect_b32 s25, s22, s30
	s_add_u32 s28, s28, 0x40080
	s_addc_u32 s29, s29, 0
	s_mov_b32 s100, 0x40000
	s_mov_b32 s101, 0
	s_add_u32 s27, s30, 0x100
	s_addc_u32 s44, s31, 0
	s_mov_b32 s45, -2
	s_add_u32 s30, s28, 0xfffc0080
	s_addc_u32 s31, s29, -1
	s_cmp_eq_u32 s45, 12
	s_cselect_b32 s35, s3, s31
	s_cselect_b32 s34, s17, s30
	s_cselect_b32 s31, s19, s44
	s_cselect_b32 s30, s25, s27
	ds_read_b128 v[108:111], v251
	ds_read_b128 v[112:115], v251 offset:1024
	ds_read_b128 v[124:127], v251 offset:2048
	ds_read_b128 v[128:131], v251 offset:3072
	ds_read_b128 v[132:135], v251 offset:16384
	ds_read_b128 v[140:143], v251 offset:17408
	ds_read_b128 v[148:151], v251 offset:18432
	ds_read_b128 v[156:159], v251 offset:19456
	v_lshl_add_u64 v[212:213], s[28:29], 0, v[208:209]
	s_add_i32 m0, s42, 0xc000
	ds_read_b128 v[164:167], v253
	ds_read_b128 v[168:171], v253 offset:1024
	ds_read_b128 v[172:175], v253 offset:2048
	ds_read_b128 v[176:179], v253 offset:3072
	ds_read_b128 v[180:183], v253 offset:4096
	ds_read_b128 v[184:187], v253 offset:5120
	ds_read_b128 v[188:191], v253 offset:6144
	ds_read_b128 v[192:195], v253 offset:7168
	global_load_lds_dwordx4 v[212:213], off
	s_add_i32 m0, s42, 0xe000
	v_lshl_add_u64 v[212:213], s[28:29], 0, v[210:211]
	global_load_lds_dwordx4 v[212:213], off
	s_waitcnt vmcnt(8) lgkmcnt(0)
	s_barrier
	s_setprio 1
	v_mfma_f32_16x16x32_bf16 v[160:163], v[108:111], v[164:167], 0
	v_mfma_f32_16x16x32_bf16 v[152:155], v[124:127], v[164:167], 0
	v_mfma_f32_16x16x32_bf16 v[120:123], v[108:111], v[172:175], 0
	v_mfma_f32_16x16x32_bf16 v[116:119], v[124:127], v[172:175], 0
	v_mfma_f32_16x16x32_bf16 v[96:99], v[108:111], v[180:183], 0
	v_mfma_f32_16x16x32_bf16 v[92:95], v[124:127], v[180:183], 0
	v_mfma_f32_16x16x32_bf16 v[80:83], v[108:111], v[188:191], 0
	v_mfma_f32_16x16x32_bf16 v[76:79], v[124:127], v[188:191], 0
	v_mfma_f32_16x16x32_bf16 v[160:163], v[112:115], v[168:171], v[160:163]
	v_mfma_f32_16x16x32_bf16 v[152:155], v[128:131], v[168:171], v[152:155]
	v_mfma_f32_16x16x32_bf16 v[120:123], v[112:115], v[176:179], v[120:123]
	v_mfma_f32_16x16x32_bf16 v[116:119], v[128:131], v[176:179], v[116:119]
	v_mfma_f32_16x16x32_bf16 v[96:99], v[112:115], v[184:187], v[96:99]
	v_mfma_f32_16x16x32_bf16 v[92:95], v[128:131], v[184:187], v[92:95]
	v_mfma_f32_16x16x32_bf16 v[80:83], v[112:115], v[192:195], v[80:83]
	v_mfma_f32_16x16x32_bf16 v[76:79], v[128:131], v[192:195], v[76:79]
	s_setprio 0
	s_setprio 1
	v_mfma_f32_16x16x32_bf16 v[144:147], v[132:135], v[164:167], 0
	v_mfma_f32_16x16x32_bf16 v[136:139], v[148:151], v[164:167], 0
	v_mfma_f32_16x16x32_bf16 v[104:107], v[132:135], v[172:175], 0
	v_mfma_f32_16x16x32_bf16 v[100:103], v[148:151], v[172:175], 0
	v_mfma_f32_16x16x32_bf16 v[88:91], v[132:135], v[180:183], 0
	v_mfma_f32_16x16x32_bf16 v[84:87], v[148:151], v[180:183], 0
	v_mfma_f32_16x16x32_bf16 v[72:75], v[132:135], v[188:191], 0
	v_mfma_f32_16x16x32_bf16 v[68:71], v[148:151], v[188:191], 0
	v_mfma_f32_16x16x32_bf16 v[144:147], v[140:143], v[168:171], v[144:147]
	v_mfma_f32_16x16x32_bf16 v[136:139], v[156:159], v[168:171], v[136:139]
	v_mfma_f32_16x16x32_bf16 v[104:107], v[140:143], v[176:179], v[104:107]
	v_mfma_f32_16x16x32_bf16 v[100:103], v[156:159], v[176:179], v[100:103]
	v_mfma_f32_16x16x32_bf16 v[88:91], v[140:143], v[184:187], v[88:91]
	v_mfma_f32_16x16x32_bf16 v[84:87], v[156:159], v[184:187], v[84:87]
	v_mfma_f32_16x16x32_bf16 v[72:75], v[140:143], v[192:195], v[72:75]
	v_mfma_f32_16x16x32_bf16 v[68:71], v[156:159], v[192:195], v[68:71]
	s_setprio 0
	s_barrier
	v_lshl_add_u64 v[212:213], s[30:31], 0, v[202:203]
	s_add_i32 m0, s41, 0x10000
	ds_read_b128 v[164:167], v253 offset:16384
	ds_read_b128 v[168:171], v253 offset:17408
	ds_read_b128 v[172:175], v253 offset:18432
	ds_read_b128 v[176:179], v253 offset:19456
	ds_read_b128 v[180:183], v253 offset:20480
	ds_read_b128 v[184:187], v253 offset:21504
	ds_read_b128 v[188:191], v253 offset:22528
	ds_read_b128 v[192:195], v253 offset:23552
	global_load_lds_dwordx4 v[212:213], off
	s_add_i32 m0, s41, 0x12000
	v_lshl_add_u64 v[214:215], s[30:31], 0, v[206:207]
	global_load_lds_dwordx4 v[214:215], off
	v_lshl_add_u64 v[216:217], v[212:213], 0, s[100:101]
	s_add_i32 m0, s41, 0x14000
	v_lshl_add_u64 v[218:219], s[34:35], 0, v[204:205]
	global_load_lds_dwordx4 v[216:217], off
	s_add_i32 m0, s41, 0x16000
	v_lshl_add_u64 v[216:217], v[214:215], 0, s[100:101]
	global_load_lds_dwordx4 v[216:217], off
	s_mov_b32 m0, s42
	v_lshl_add_u64 v[216:217], s[34:35], 0, v[0:1]
	global_load_lds_dwordx4 v[216:217], off
	s_mov_b32 m0, s43
	s_add_i32 s52, 0, 0x18000
	global_load_lds_dwordx4 v[218:219], off
	s_waitcnt vmcnt(8) lgkmcnt(0)
	s_barrier
; #define PG8_STAGE(bufoff, gbase, voff) do { _Pragma("unroll") for (int _i = 0; _i < 2; ++_i) \
;         __builtin_amdgcn_global_load_lds((const unsigned*)((const char*)(gbase) + (voff)[_i]), (PG8_LAS unsigned*)(lds + (bufoff) + ldsw + _i * 8192), 16, 0, 0); } while (0)
; #define PG8_LDA(dst, b, h) do { _Pragma("unroll") for (int m = 0; m < 4; ++m) _Pragma("unroll") for (int k = 0; k < 2; ++k) dst[m][k] = *(const PG8_LAS bf16x8*)(lds + PG8_SA(b, h) + aoff + m * 2048 + k * 1024); } while (0)
; #define PG8_LDB(dst, b, h) do { _Pragma("unroll") for (int n = 0; n < 2; ++n) _Pragma("unroll") for (int k = 0; k < 2; ++k) dst[n][k] = *(const PG8_LAS bf16x8*)(lds + PG8_SB(b, h) + boff + n * 2048 + k * 1024); } while (0)
; #define PG8_MMA(ai, bj, At, Bt) do { __builtin_amdgcn_s_setprio(1); _Pragma("unroll") for (int m = 0; m < 4; ++m) _Pragma("unroll") for (int n = 0; n < 2; ++n) _Pragma("unroll") for (int k = 0; k < 2; ++k) \
;         acc[ai][bj][m][n] = __builtin_amdgcn_mfma_f32_16x16x32_bf16(Bt[n][k], At[m][k], acc[ai][bj][m][n], 0, 0, 0); __builtin_amdgcn_s_setprio(0); } while (0)
; #define PG8_WAIT_V(n) asm volatile("s_waitcnt vmcnt(" #n ")" ::: "memory")
; #define PG8_WAIT_L(n) asm volatile("s_waitcnt lgkmcnt(" #n ")" ::: "memory")
; #define PG8_BAR __builtin_amdgcn_s_barrier()
; #define PG8_SCHED __builtin_amdgcn_sched_barrier(0)
; template <class Epi, class Sched, bool ALIGN_EPI = false, bool SP2 = false>
; __device__ __forceinline__ void gemm_phase(PG8_LAS unsigned char* lds, const Gemm g, const Sched& S, const Epi& E) {
;     ...
;             PG8_LDB(B0, 0, 0); PG8_LDB(B1, 0, 1); PG8_SCHED; PG8_LDA(At, 0, 0); PG8_STAGE(PG8_SA(1, 1), a1 + hstep, voffA);
;             PG8_WAIT_V(8); PG8_WAIT_L(0); PG8_BAR; PG8_MMA(0, 0, At, B0); PG8_MMA(0, 1, At, B1); PG8_BAR; PG8_SCHED;
;             PG8_LDA(At, 0, 1); PG8_STAGE(PG8_SB(0, 0), b2, voffB); PG8_STAGE(PG8_SB(0, 1), b2 + hstep, voffB); PG8_STAGE(PG8_SA(0, 0), a2, voffA);
;             PG8_WAIT_V(8); PG8_WAIT_L(0); PG8_BAR; PG8_MMA(1, 0, At, B0); PG8_MMA(1, 1, At, B1); PG8_BAR; PG8_SCHED;
	s_setprio 1
	v_mfma_f32_16x16x32_bf16 v[64:67], v[108:111], v[164:167], 0
	v_mfma_f32_16x16x32_bf16 v[60:63], v[124:127], v[164:167], 0
	v_mfma_f32_16x16x32_bf16 v[48:51], v[108:111], v[172:175], 0
	v_mfma_f32_16x16x32_bf16 v[44:47], v[124:127], v[172:175], 0
	v_mfma_f32_16x16x32_bf16 v[32:35], v[108:111], v[180:183], 0
	v_mfma_f32_16x16x32_bf16 v[28:31], v[124:127], v[180:183], 0
	v_mfma_f32_16x16x32_bf16 v[16:19], v[108:111], v[188:191], 0
	v_mfma_f32_16x16x32_bf16 v[12:15], v[124:127], v[188:191], 0
	v_mfma_f32_16x16x32_bf16 v[64:67], v[112:115], v[168:171], v[64:67]
	v_mfma_f32_16x16x32_bf16 v[60:63], v[128:131], v[168:171], v[60:63]
	v_mfma_f32_16x16x32_bf16 v[48:51], v[112:115], v[176:179], v[48:51]
	v_mfma_f32_16x16x32_bf16 v[44:47], v[128:131], v[176:179], v[44:47]
	v_mfma_f32_16x16x32_bf16 v[32:35], v[112:115], v[184:187], v[32:35]
	v_mfma_f32_16x16x32_bf16 v[28:31], v[128:131], v[184:187], v[28:31]
	v_mfma_f32_16x16x32_bf16 v[16:19], v[112:115], v[192:195], v[16:19]
	v_mfma_f32_16x16x32_bf16 v[12:15], v[128:131], v[192:195], v[12:15]
	s_setprio 0
	s_setprio 1
	v_mfma_f32_16x16x32_bf16 v[56:59], v[132:135], v[164:167], 0
	v_mfma_f32_16x16x32_bf16 v[52:55], v[148:151], v[164:167], 0
	v_mfma_f32_16x16x32_bf16 v[40:43], v[132:135], v[172:175], 0
	v_mfma_f32_16x16x32_bf16 v[36:39], v[148:151], v[172:175], 0
	v_mfma_f32_16x16x32_bf16 v[24:27], v[132:135], v[180:183], 0
	v_mfma_f32_16x16x32_bf16 v[20:23], v[148:151], v[180:183], 0
	v_mfma_f32_16x16x32_bf16 v[8:11], v[132:135], v[188:191], 0
	v_mfma_f32_16x16x32_bf16 v[4:7], v[148:151], v[188:191], 0
	v_mfma_f32_16x16x32_bf16 v[56:59], v[140:143], v[168:171], v[56:59]
	v_mfma_f32_16x16x32_bf16 v[52:55], v[156:159], v[168:171], v[52:55]
	v_mfma_f32_16x16x32_bf16 v[40:43], v[140:143], v[176:179], v[40:43]
	v_mfma_f32_16x16x32_bf16 v[36:39], v[156:159], v[176:179], v[36:39]
	v_mfma_f32_16x16x32_bf16 v[24:27], v[140:143], v[184:187], v[24:27]
	v_mfma_f32_16x16x32_bf16 v[20:23], v[156:159], v[184:187], v[20:23]
	v_mfma_f32_16x16x32_bf16 v[8:11], v[140:143], v[192:195], v[8:11]
	v_mfma_f32_16x16x32_bf16 v[4:7], v[156:159], v[192:195], v[4:7]
	s_setprio 0
	s_barrier
	s_branch .Lkmid_1
.LBB0_329:
	s_add_u32 s30, s28, 0xfffc0080
	s_addc_u32 s31, s29, -1
	s_cmp_eq_u32 s45, 12
	s_cselect_b32 s35, s3, s31
	s_cselect_b32 s34, s17, s30
	s_cselect_b32 s31, s19, s44
	s_cselect_b32 s30, s25, s27
	ds_read_b128 v[108:111], v251
	ds_read_b128 v[112:115], v251 offset:1024
	ds_read_b128 v[124:127], v251 offset:2048
	ds_read_b128 v[128:131], v251 offset:3072
	ds_read_b128 v[132:135], v251 offset:16384
	ds_read_b128 v[140:143], v251 offset:17408
	ds_read_b128 v[148:151], v251 offset:18432
	ds_read_b128 v[156:159], v251 offset:19456
	v_lshl_add_u64 v[212:213], s[28:29], 0, v[208:209]
	s_add_i32 m0, s42, 0xc000
	ds_read_b128 v[164:167], v253
	ds_read_b128 v[168:171], v253 offset:1024
	ds_read_b128 v[172:175], v253 offset:2048
	ds_read_b128 v[176:179], v253 offset:3072
	ds_read_b128 v[180:183], v253 offset:4096
	ds_read_b128 v[184:187], v253 offset:5120
	ds_read_b128 v[188:191], v253 offset:6144
	ds_read_b128 v[192:195], v253 offset:7168
	global_load_lds_dwordx4 v[212:213], off
	s_add_i32 m0, s42, 0xe000
	v_lshl_add_u64 v[212:213], s[28:29], 0, v[210:211]
	global_load_lds_dwordx4 v[212:213], off
	s_waitcnt vmcnt(8) lgkmcnt(0)
	s_barrier
	s_setprio 1
	v_mfma_f32_16x16x32_bf16 v[160:163], v[108:111], v[164:167], v[160:163]
	v_mfma_f32_16x16x32_bf16 v[152:155], v[124:127], v[164:167], v[152:155]
	v_mfma_f32_16x16x32_bf16 v[120:123], v[108:111], v[172:175], v[120:123]
	v_mfma_f32_16x16x32_bf16 v[116:119], v[124:127], v[172:175], v[116:119]
	v_mfma_f32_16x16x32_bf16 v[96:99], v[108:111], v[180:183], v[96:99]
	v_mfma_f32_16x16x32_bf16 v[92:95], v[124:127], v[180:183], v[92:95]
	v_mfma_f32_16x16x32_bf16 v[80:83], v[108:111], v[188:191], v[80:83]
	v_mfma_f32_16x16x32_bf16 v[76:79], v[124:127], v[188:191], v[76:79]
	v_mfma_f32_16x16x32_bf16 v[160:163], v[112:115], v[168:171], v[160:163]
	v_mfma_f32_16x16x32_bf16 v[152:155], v[128:131], v[168:171], v[152:155]
	v_mfma_f32_16x16x32_bf16 v[120:123], v[112:115], v[176:179], v[120:123]
	v_mfma_f32_16x16x32_bf16 v[116:119], v[128:131], v[176:179], v[116:119]
	v_mfma_f32_16x16x32_bf16 v[96:99], v[112:115], v[184:187], v[96:99]
	v_mfma_f32_16x16x32_bf16 v[92:95], v[128:131], v[184:187], v[92:95]
	v_mfma_f32_16x16x32_bf16 v[80:83], v[112:115], v[192:195], v[80:83]
	v_mfma_f32_16x16x32_bf16 v[76:79], v[128:131], v[192:195], v[76:79]
	s_setprio 0
	s_setprio 1
	v_mfma_f32_16x16x32_bf16 v[144:147], v[132:135], v[164:167], v[144:147]
	v_mfma_f32_16x16x32_bf16 v[136:139], v[148:151], v[164:167], v[136:139]
	v_mfma_f32_16x16x32_bf16 v[104:107], v[132:135], v[172:175], v[104:107]
	v_mfma_f32_16x16x32_bf16 v[100:103], v[148:151], v[172:175], v[100:103]
	v_mfma_f32_16x16x32_bf16 v[88:91], v[132:135], v[180:183], v[88:91]
	v_mfma_f32_16x16x32_bf16 v[84:87], v[148:151], v[180:183], v[84:87]
	v_mfma_f32_16x16x32_bf16 v[72:75], v[132:135], v[188:191], v[72:75]
	v_mfma_f32_16x16x32_bf16 v[68:71], v[148:151], v[188:191], v[68:71]
	v_mfma_f32_16x16x32_bf16 v[144:147], v[140:143], v[168:171], v[144:147]
	v_mfma_f32_16x16x32_bf16 v[136:139], v[156:159], v[168:171], v[136:139]
	v_mfma_f32_16x16x32_bf16 v[104:107], v[140:143], v[176:179], v[104:107]
	v_mfma_f32_16x16x32_bf16 v[100:103], v[156:159], v[176:179], v[100:103]
	v_mfma_f32_16x16x32_bf16 v[88:91], v[140:143], v[184:187], v[88:91]
	v_mfma_f32_16x16x32_bf16 v[84:87], v[156:159], v[184:187], v[84:87]
	v_mfma_f32_16x16x32_bf16 v[72:75], v[140:143], v[192:195], v[72:75]
	v_mfma_f32_16x16x32_bf16 v[68:71], v[156:159], v[192:195], v[68:71]
	s_setprio 0
	s_barrier
; #define PG8_STAGE(bufoff, gbase, voff) do { _Pragma("unroll") for (int _i = 0; _i < 2; ++_i) \
;         __builtin_amdgcn_global_load_lds((const unsigned*)((const char*)(gbase) + (voff)[_i]), (PG8_LAS unsigned*)(lds + (bufoff) + ldsw + _i * 8192), 16, 0, 0); } while (0)
; #define PG8_LDA(dst, b, h) do { _Pragma("unroll") for (int m = 0; m < 4; ++m) _Pragma("unroll") for (int k = 0; k < 2; ++k) dst[m][k] = *(const PG8_LAS bf16x8*)(lds + PG8_SA(b, h) + aoff + m * 2048 + k * 1024); } while (0)
; #define PG8_MMA(ai, bj, At, Bt) do { __builtin_amdgcn_s_setprio(1); _Pragma("unroll") for (int m = 0; m < 4; ++m) _Pragma("unroll") for (int n = 0; n < 2; ++n) _Pragma("unroll") for (int k = 0; k < 2; ++k) \
;         acc[ai][bj][m][n] = __builtin_amdgcn_mfma_f32_16x16x32_bf16(Bt[n][k], At[m][k], acc[ai][bj][m][n], 0, 0, 0); __builtin_amdgcn_s_setprio(0); } while (0)
; #define PG8_WAIT_V(n) asm volatile("s_waitcnt vmcnt(" #n ")" ::: "memory")
; #define PG8_WAIT_L(n) asm volatile("s_waitcnt lgkmcnt(" #n ")" ::: "memory")
; #define PG8_BAR __builtin_amdgcn_s_barrier()
; #define PG8_SCHED __builtin_amdgcn_sched_barrier(0)
; template <class Epi, class Sched, bool ALIGN_EPI = false, bool SP2 = false>
; __device__ __forceinline__ void gemm_phase(PG8_LAS unsigned char* lds, const Gemm g, const Sched& S, const Epi& E) {
;     ...
;             PG8_LDA(At, 0, 1); PG8_STAGE(PG8_SB(0, 0), b2, voffB); PG8_STAGE(PG8_SB(0, 1), b2 + hstep, voffB); PG8_STAGE(PG8_SA(0, 0), a2, voffA);
;             PG8_WAIT_V(8); PG8_WAIT_L(0); PG8_BAR; PG8_MMA(1, 0, At, B0); PG8_MMA(1, 1, At, B1); PG8_BAR; PG8_SCHED;
	v_lshl_add_u64 v[212:213], s[30:31], 0, v[202:203]
	s_add_i32 m0, s41, 0x10000
	ds_read_b128 v[164:167], v253 offset:16384
	ds_read_b128 v[168:171], v253 offset:17408
	ds_read_b128 v[172:175], v253 offset:18432
	ds_read_b128 v[176:179], v253 offset:19456
	ds_read_b128 v[180:183], v253 offset:20480
	ds_read_b128 v[184:187], v253 offset:21504
	ds_read_b128 v[188:191], v253 offset:22528
	ds_read_b128 v[192:195], v253 offset:23552
	global_load_lds_dwordx4 v[212:213], off
	s_add_i32 m0, s41, 0x12000
	v_lshl_add_u64 v[214:215], s[30:31], 0, v[206:207]
	global_load_lds_dwordx4 v[214:215], off
	v_lshl_add_u64 v[216:217], v[212:213], 0, s[100:101]
	s_add_i32 m0, s41, 0x14000
	v_lshl_add_u64 v[218:219], s[34:35], 0, v[204:205]
	global_load_lds_dwordx4 v[216:217], off
	s_add_i32 m0, s41, 0x16000
	v_lshl_add_u64 v[216:217], v[214:215], 0, s[100:101]
	global_load_lds_dwordx4 v[216:217], off
	s_mov_b32 m0, s42
	v_lshl_add_u64 v[216:217], s[34:35], 0, v[0:1]
	global_load_lds_dwordx4 v[216:217], off
	s_mov_b32 m0, s43
	s_add_i32 s52, 0, 0x18000
	global_load_lds_dwordx4 v[218:219], off
	s_waitcnt vmcnt(8) lgkmcnt(0)
	s_barrier
	s_setprio 1
	v_mfma_f32_16x16x32_bf16 v[64:67], v[108:111], v[164:167], v[64:67]
	v_mfma_f32_16x16x32_bf16 v[60:63], v[124:127], v[164:167], v[60:63]
	v_mfma_f32_16x16x32_bf16 v[48:51], v[108:111], v[172:175], v[48:51]
	v_mfma_f32_16x16x32_bf16 v[44:47], v[124:127], v[172:175], v[44:47]
	v_mfma_f32_16x16x32_bf16 v[32:35], v[108:111], v[180:183], v[32:35]
	v_mfma_f32_16x16x32_bf16 v[28:31], v[124:127], v[180:183], v[28:31]
	v_mfma_f32_16x16x32_bf16 v[16:19], v[108:111], v[188:191], v[16:19]
	v_mfma_f32_16x16x32_bf16 v[12:15], v[124:127], v[188:191], v[12:15]
	v_mfma_f32_16x16x32_bf16 v[64:67], v[112:115], v[168:171], v[64:67]
	v_mfma_f32_16x16x32_bf16 v[60:63], v[128:131], v[168:171], v[60:63]
	v_mfma_f32_16x16x32_bf16 v[48:51], v[112:115], v[176:179], v[48:51]
	v_mfma_f32_16x16x32_bf16 v[44:47], v[128:131], v[176:179], v[44:47]
	v_mfma_f32_16x16x32_bf16 v[32:35], v[112:115], v[184:187], v[32:35]
	v_mfma_f32_16x16x32_bf16 v[28:31], v[128:131], v[184:187], v[28:31]
	v_mfma_f32_16x16x32_bf16 v[16:19], v[112:115], v[192:195], v[16:19]
	v_mfma_f32_16x16x32_bf16 v[12:15], v[128:131], v[192:195], v[12:15]
	s_setprio 0
	s_setprio 1
	v_mfma_f32_16x16x32_bf16 v[56:59], v[132:135], v[164:167], v[56:59]
	v_mfma_f32_16x16x32_bf16 v[52:55], v[148:151], v[164:167], v[52:55]
	v_mfma_f32_16x16x32_bf16 v[40:43], v[132:135], v[172:175], v[40:43]
	v_mfma_f32_16x16x32_bf16 v[36:39], v[148:151], v[172:175], v[36:39]
	v_mfma_f32_16x16x32_bf16 v[24:27], v[132:135], v[180:183], v[24:27]
	v_mfma_f32_16x16x32_bf16 v[20:23], v[148:151], v[180:183], v[20:23]
	v_mfma_f32_16x16x32_bf16 v[8:11], v[132:135], v[188:191], v[8:11]
	v_mfma_f32_16x16x32_bf16 v[4:7], v[148:151], v[188:191], v[4:7]
	v_mfma_f32_16x16x32_bf16 v[56:59], v[140:143], v[168:171], v[56:59]
	v_mfma_f32_16x16x32_bf16 v[52:55], v[156:159], v[168:171], v[52:55]
	v_mfma_f32_16x16x32_bf16 v[40:43], v[140:143], v[176:179], v[40:43]
	v_mfma_f32_16x16x32_bf16 v[36:39], v[156:159], v[176:179], v[36:39]
	v_mfma_f32_16x16x32_bf16 v[24:27], v[140:143], v[184:187], v[24:27]
	v_mfma_f32_16x16x32_bf16 v[20:23], v[156:159], v[184:187], v[20:23]
	v_mfma_f32_16x16x32_bf16 v[8:11], v[140:143], v[192:195], v[8:11]
	v_mfma_f32_16x16x32_bf16 v[4:7], v[156:159], v[192:195], v[4:7]
	s_setprio 0
	s_barrier
; #define PG8_STAGE(bufoff, gbase, voff) do { _Pragma("unroll") for (int _i = 0; _i < 2; ++_i) \
;         __builtin_amdgcn_global_load_lds((const unsigned*)((const char*)(gbase) + (voff)[_i]), (PG8_LAS unsigned*)(lds + (bufoff) + ldsw + _i * 8192), 16, 0, 0); } while (0)
; #define PG8_LDA(dst, b, h) do { _Pragma("unroll") for (int m = 0; m < 4; ++m) _Pragma("unroll") for (int k = 0; k < 2; ++k) dst[m][k] = *(const PG8_LAS bf16x8*)(lds + PG8_SA(b, h) + aoff + m * 2048 + k * 1024); } while (0)
; #define PG8_LDB(dst, b, h) do { _Pragma("unroll") for (int n = 0; n < 2; ++n) _Pragma("unroll") for (int k = 0; k < 2; ++k) dst[n][k] = *(const PG8_LAS bf16x8*)(lds + PG8_SB(b, h) + boff + n * 2048 + k * 1024); } while (0)
; template <class Epi, class Sched, bool ALIGN_EPI = false, bool SP2 = false>
; __device__ __forceinline__ void gemm_phase(PG8_LAS unsigned char* lds, const Gemm g, const Sched& S, const Epi& E) {
;     ...
;         for (int t = 0; t < nt; t += 2) {
;             const bool last = (t == nt - 2);
;             const char* a1 = cA + (size_t)(t + 1) * kstep;
;             const char* a2 = last ? nA : cA + (size_t)(t + 2) * kstep; const char* b2 = last ? nB : cB + (size_t)(t + 2) * kstep;
;             const char* a3 = a2 + kstep; const char* b3 = b2 + kstep;
;             if (last && has_next) S.a_ready(nxt);
;             if constexpr (SP2) {
;             PG8_LDB(B0, 0, 0); PG8_LDB(B1, 0, 1); PG8_SCHED; PG8_LDA(At, 0, 0); PG8_STAGE(PG8_SA(1, 1), a1 + hstep, voffA);
;             PG8_WAIT_V(8); PG8_WAIT_L(0); PG8_BAR; PG8_MMA(0, 0, At, B0); PG8_MMA(0, 1, At, B1); PG8_BAR; PG8_SCHED;
;             PG8_LDA(At, 0, 1); PG8_STAGE(PG8_SB(0, 0), b2, voffB); PG8_STAGE(PG8_SB(0, 1), b2 + hstep, voffB); PG8_STAGE(PG8_SA(0, 0), a2, voffA);
;             PG8_WAIT_V(8); PG8_WAIT_L(0); PG8_BAR; PG8_MMA(1, 0, At, B0); PG8_MMA(1, 1, At, B1); PG8_BAR; PG8_SCHED;
;             PG8_LDB(B0, 1, 0); PG8_LDB(B1, 1, 1); PG8_SCHED; PG8_LDA(At, 1, 0); PG8_STAGE(PG8_SA(0, 1), a2 + hstep, voffA);
;             PG8_WAIT_V(8); PG8_WAIT_L(0); PG8_BAR; PG8_MMA(0, 0, At, B0); PG8_MMA(0, 1, At, B1); PG8_BAR; PG8_SCHED;
;             PG8_LDA(At, 1, 1); PG8_STAGE(PG8_SB(1, 0), b3, voffB); PG8_STAGE(PG8_SB(1, 1), b3 + hstep, voffB); PG8_STAGE(PG8_SA(1, 0), a3, voffA);
;             PG8_WAIT_V(8); PG8_WAIT_L(0); PG8_BAR; PG8_MMA(1, 0, At, B0); PG8_MMA(1, 1, At, B1); PG8_BAR; PG8_SCHED;
.Lkmid_1:
	ds_read_b128 v[108:111], v251 offset:32768
	ds_read_b128 v[112:115], v251 offset:33792
	ds_read_b128 v[124:127], v251 offset:34816
	ds_read_b128 v[128:131], v251 offset:35840
	ds_read_b128 v[132:135], v251 offset:49152
	ds_read_b128 v[140:143], v251 offset:50176
	ds_read_b128 v[148:151], v251 offset:51200
	ds_read_b128 v[156:159], v251 offset:52224
	s_mov_b32 m0, s46
	v_lshl_add_u64 v[220:221], v[216:217], 0, s[100:101]
	ds_read_b128 v[164:167], v253 offset:32768
	ds_read_b128 v[168:171], v253 offset:33792
	ds_read_b128 v[172:175], v253 offset:34816
	ds_read_b128 v[176:179], v253 offset:35840
	ds_read_b128 v[180:183], v253 offset:36864
	ds_read_b128 v[184:187], v253 offset:37888
	ds_read_b128 v[188:191], v253 offset:38912
	ds_read_b128 v[192:195], v253 offset:39936
	global_load_lds_dwordx4 v[220:221], off
	s_mov_b32 m0, s47
	v_lshl_add_u64 v[220:221], v[218:219], 0, s[100:101]
	global_load_lds_dwordx4 v[220:221], off
	s_waitcnt vmcnt(8) lgkmcnt(0)
	s_barrier
	s_setprio 1
	v_mfma_f32_16x16x32_bf16 v[160:163], v[108:111], v[164:167], v[160:163]
	v_mfma_f32_16x16x32_bf16 v[152:155], v[124:127], v[164:167], v[152:155]
	v_mfma_f32_16x16x32_bf16 v[120:123], v[108:111], v[172:175], v[120:123]
	v_mfma_f32_16x16x32_bf16 v[116:119], v[124:127], v[172:175], v[116:119]
	v_mfma_f32_16x16x32_bf16 v[96:99], v[108:111], v[180:183], v[96:99]
	v_mfma_f32_16x16x32_bf16 v[92:95], v[124:127], v[180:183], v[92:95]
	v_mfma_f32_16x16x32_bf16 v[80:83], v[108:111], v[188:191], v[80:83]
	v_mfma_f32_16x16x32_bf16 v[76:79], v[124:127], v[188:191], v[76:79]
	v_mfma_f32_16x16x32_bf16 v[160:163], v[112:115], v[168:171], v[160:163]
	v_mfma_f32_16x16x32_bf16 v[152:155], v[128:131], v[168:171], v[152:155]
	v_mfma_f32_16x16x32_bf16 v[120:123], v[112:115], v[176:179], v[120:123]
	v_mfma_f32_16x16x32_bf16 v[116:119], v[128:131], v[176:179], v[116:119]
	v_mfma_f32_16x16x32_bf16 v[96:99], v[112:115], v[184:187], v[96:99]
	v_mfma_f32_16x16x32_bf16 v[92:95], v[128:131], v[184:187], v[92:95]
	v_mfma_f32_16x16x32_bf16 v[80:83], v[112:115], v[192:195], v[80:83]
	v_mfma_f32_16x16x32_bf16 v[76:79], v[128:131], v[192:195], v[76:79]
	s_setprio 0
	s_setprio 1
	v_mfma_f32_16x16x32_bf16 v[144:147], v[132:135], v[164:167], v[144:147]
	v_mfma_f32_16x16x32_bf16 v[136:139], v[148:151], v[164:167], v[136:139]
	v_mfma_f32_16x16x32_bf16 v[104:107], v[132:135], v[172:175], v[104:107]
	v_mfma_f32_16x16x32_bf16 v[100:103], v[148:151], v[172:175], v[100:103]
	v_mfma_f32_16x16x32_bf16 v[88:91], v[132:135], v[180:183], v[88:91]
	v_mfma_f32_16x16x32_bf16 v[84:87], v[148:151], v[180:183], v[84:87]
	v_mfma_f32_16x16x32_bf16 v[72:75], v[132:135], v[188:191], v[72:75]
	v_mfma_f32_16x16x32_bf16 v[68:71], v[148:151], v[188:191], v[68:71]
	v_mfma_f32_16x16x32_bf16 v[144:147], v[140:143], v[168:171], v[144:147]
	v_mfma_f32_16x16x32_bf16 v[136:139], v[156:159], v[168:171], v[136:139]
	v_mfma_f32_16x16x32_bf16 v[104:107], v[140:143], v[176:179], v[104:107]
	v_mfma_f32_16x16x32_bf16 v[100:103], v[156:159], v[176:179], v[100:103]
	v_mfma_f32_16x16x32_bf16 v[88:91], v[140:143], v[184:187], v[88:91]
	v_mfma_f32_16x16x32_bf16 v[84:87], v[156:159], v[184:187], v[84:87]
	v_mfma_f32_16x16x32_bf16 v[72:75], v[140:143], v[192:195], v[72:75]
	v_mfma_f32_16x16x32_bf16 v[68:71], v[156:159], v[192:195], v[68:71]
	s_setprio 0
	s_barrier
	s_add_i32 m0, s41, 0x17f80
	ds_read_b128 v[164:167], v253 offset:49152
	ds_read_b128 v[168:171], v253 offset:50176
	ds_read_b128 v[172:175], v253 offset:51200
	ds_read_b128 v[176:179], v253 offset:52224
	ds_read_b128 v[180:183], v253 offset:53248
	ds_read_b128 v[184:187], v253 offset:54272
	ds_read_b128 v[188:191], v253 offset:55296
	ds_read_b128 v[192:195], v253 offset:56320
	global_load_lds_dwordx4 v[212:213], off offset:128
	s_add_i32 m0, s41, 0x19f80
	v_lshl_add_u64 v[212:213], v[212:213], 0, s[100:101]
	global_load_lds_dwordx4 v[214:215], off offset:128
	s_add_i32 m0, s41, 0x1bf80
	v_lshl_add_u64 v[220:221], v[214:215], 0, s[100:101]
	global_load_lds_dwordx4 v[212:213], off offset:128
	s_add_i32 m0, s41, 0x1df80
	s_add_i32 s45, s45, 2
	global_load_lds_dwordx4 v[220:221], off offset:128
	s_add_i32 m0, s49, 0xffffff80
	s_add_u32 s28, s28, 0x100
	s_addc_u32 s29, s29, 0
	global_load_lds_dwordx4 v[216:217], off offset:128
	s_add_i32 m0, s50, 0xffffff80
	s_add_u32 s27, s27, 0x100
	s_addc_u32 s44, s44, 0
	global_load_lds_dwordx4 v[218:219], off offset:128
	s_waitcnt vmcnt(8) lgkmcnt(0)
	s_barrier
	s_setprio 1
	v_mfma_f32_16x16x32_bf16 v[64:67], v[108:111], v[164:167], v[64:67]
	v_mfma_f32_16x16x32_bf16 v[60:63], v[124:127], v[164:167], v[60:63]
	v_mfma_f32_16x16x32_bf16 v[48:51], v[108:111], v[172:175], v[48:51]
	v_mfma_f32_16x16x32_bf16 v[44:47], v[124:127], v[172:175], v[44:47]
	v_mfma_f32_16x16x32_bf16 v[32:35], v[108:111], v[180:183], v[32:35]
	v_mfma_f32_16x16x32_bf16 v[28:31], v[124:127], v[180:183], v[28:31]
	v_mfma_f32_16x16x32_bf16 v[16:19], v[108:111], v[188:191], v[16:19]
	v_mfma_f32_16x16x32_bf16 v[12:15], v[124:127], v[188:191], v[12:15]
	v_mfma_f32_16x16x32_bf16 v[64:67], v[112:115], v[168:171], v[64:67]
	v_mfma_f32_16x16x32_bf16 v[60:63], v[128:131], v[168:171], v[60:63]
	v_mfma_f32_16x16x32_bf16 v[48:51], v[112:115], v[176:179], v[48:51]
	v_mfma_f32_16x16x32_bf16 v[44:47], v[128:131], v[176:179], v[44:47]
	v_mfma_f32_16x16x32_bf16 v[32:35], v[112:115], v[184:187], v[32:35]
	v_mfma_f32_16x16x32_bf16 v[28:31], v[128:131], v[184:187], v[28:31]
	v_mfma_f32_16x16x32_bf16 v[16:19], v[112:115], v[192:195], v[16:19]
	v_mfma_f32_16x16x32_bf16 v[12:15], v[128:131], v[192:195], v[12:15]
	s_setprio 0
	s_setprio 1
	v_mfma_f32_16x16x32_bf16 v[56:59], v[132:135], v[164:167], v[56:59]
	v_mfma_f32_16x16x32_bf16 v[52:55], v[148:151], v[164:167], v[52:55]
	v_mfma_f32_16x16x32_bf16 v[40:43], v[132:135], v[172:175], v[40:43]
	v_mfma_f32_16x16x32_bf16 v[36:39], v[148:151], v[172:175], v[36:39]
	v_mfma_f32_16x16x32_bf16 v[24:27], v[132:135], v[180:183], v[24:27]
	v_mfma_f32_16x16x32_bf16 v[20:23], v[148:151], v[180:183], v[20:23]
	v_mfma_f32_16x16x32_bf16 v[8:11], v[132:135], v[188:191], v[8:11]
	v_mfma_f32_16x16x32_bf16 v[4:7], v[148:151], v[188:191], v[4:7]
	v_mfma_f32_16x16x32_bf16 v[56:59], v[140:143], v[168:171], v[56:59]
	v_mfma_f32_16x16x32_bf16 v[52:55], v[156:159], v[168:171], v[52:55]
	v_mfma_f32_16x16x32_bf16 v[40:43], v[140:143], v[176:179], v[40:43]
	v_mfma_f32_16x16x32_bf16 v[36:39], v[156:159], v[176:179], v[36:39]
	v_mfma_f32_16x16x32_bf16 v[24:27], v[140:143], v[184:187], v[24:27]
	v_mfma_f32_16x16x32_bf16 v[20:23], v[156:159], v[184:187], v[20:23]
	v_mfma_f32_16x16x32_bf16 v[8:11], v[140:143], v[192:195], v[8:11]
	v_mfma_f32_16x16x32_bf16 v[4:7], v[156:159], v[192:195], v[4:7]
	s_setprio 0
	s_barrier
	s_cmp_gt_u32 s45, 13
	s_cbranch_scc0 .LBB0_329
	s_and_b64 vcc, exec, s[14:15]
	s_cbranch_vccz .LBB0_332
	s_barrier

; #define PG8_STAGE(bufoff, gbase, voff) do { _Pragma("unroll") for (int _i = 0; _i < 2; ++_i) \
;         __builtin_amdgcn_global_load_lds((const unsigned*)((const char*)(gbase) + (voff)[_i]), (PG8_LAS unsigned*)(lds + (bufoff) + ldsw + _i * 8192), 16, 0, 0); } while (0)
; #define PG8_LDA(dst, b, h) do { _Pragma("unroll") for (int m = 0; m < 4; ++m) _Pragma("unroll") for (int k = 0; k < 2; ++k) dst[m][k] = *(const PG8_LAS bf16x8*)(lds + PG8_SA(b, h) + aoff + m * 2048 + k * 1024); } while (0)
; #define PG8_LDB(dst, b, h) do { _Pragma("unroll") for (int n = 0; n < 2; ++n) _Pragma("unroll") for (int k = 0; k < 2; ++k) dst[n][k] = *(const PG8_LAS bf16x8*)(lds + PG8_SB(b, h) + boff + n * 2048 + k * 1024); } while (0)
; #define PG8_WAIT_V(n) asm volatile("s_waitcnt vmcnt(" #n ")" ::: "memory")
; #define PG8_WAIT_L(n) asm volatile("s_waitcnt lgkmcnt(" #n ")" ::: "memory")
; #define PG8_BAR __builtin_amdgcn_s_barrier()
; #define PG8_SCHED __builtin_amdgcn_sched_barrier(0)
; template <class Epi, class Sched, bool ALIGN_EPI = false, bool SP2 = false>
; __device__ __forceinline__ void gemm_phase(PG8_LAS unsigned char* lds, const Gemm g, const Sched& S, const Epi& E) {
;     ...
;         const bool has_next = S.next(ui + 1, nxt);
;         const char* nA = has_next ? (const char*)g.A + (size_t)nxt.pm * tstep : cA; const char* nB = has_next ? (const char*)g.Bt + (size_t)nxt.pn * tstep : cB;
;         for (int t = 0; t < nt; t += 2) {
;             const bool last = (t == nt - 2);
;             const char* a1 = cA + (size_t)(t + 1) * kstep;
;             const char* a2 = last ? nA : cA + (size_t)(t + 2) * kstep; const char* b2 = last ? nB : cB + (size_t)(t + 2) * kstep;
;             const char* a3 = a2 + kstep; const char* b3 = b2 + kstep;
;             if (last && has_next) S.a_ready(nxt);
;             if constexpr (SP2) {
;             PG8_LDB(B0, 0, 0); PG8_LDB(B1, 0, 1); PG8_SCHED; PG8_LDA(At, 0, 0); PG8_STAGE(PG8_SA(1, 1), a1 + hstep, voffA);
;             PG8_WAIT_V(8); PG8_WAIT_L(0); PG8_BAR; PG8_MMA(0, 0, At, B0); PG8_MMA(0, 1, At, B1); PG8_BAR; PG8_SCHED;
;             PG8_LDA(At, 0, 1); PG8_STAGE(PG8_SB(0, 0), b2, voffB); PG8_STAGE(PG8_SB(0, 1), b2 + hstep, voffB); PG8_STAGE(PG8_SA(0, 0), a2, voffA);
;             PG8_WAIT_V(8); PG8_WAIT_L(0); PG8_BAR; PG8_MMA(1, 0, At, B0); PG8_MMA(1, 1, At, B1); PG8_BAR; PG8_SCHED;
.LBB0_404:
	s_ashr_i32 s17, s16, 31
	s_lshl_b64 s[20:21], s[16:17], 19
	s_add_u32 s20, s29, s20
	s_addc_u32 s21, s30, s21
	s_and_b64 s[22:23], s[4:5], exec
	s_cselect_b32 s7, s21, s9
	s_cselect_b32 s17, s20, s8
	s_ashr_i32 s19, s18, 31
	s_lshl_b64 s[22:23], s[18:19], 19
	s_add_u32 s22, s31, s22
	s_addc_u32 s23, s34, s23
	s_and_b64 s[26:27], s[4:5], exec
	s_cselect_b32 s19, s23, s25
	s_cselect_b32 s43, s22, s24
	s_add_u32 s8, s8, 0x40080
	s_addc_u32 s9, s9, 0
	s_mov_b32 s100, 0x40000
	s_mov_b32 s101, 0
	s_add_u32 s44, s24, 0x100
	s_addc_u32 s45, s25, 0
	s_mov_b32 s46, -2
	s_add_u32 s24, s8, 0xfffc0080
	s_addc_u32 s25, s9, -1
	s_cmp_eq_u32 s46, 12
	s_cselect_b32 s27, s7, s25
	s_cselect_b32 s26, s17, s24
	s_cselect_b32 s25, s19, s45
	s_cselect_b32 s24, s43, s44
	s_add_i32 s50, 0, 0x14000
	ds_read_b128 v[144:147], v164
	ds_read_b128 v[148:151], v164 offset:1024
	ds_read_b128 v[152:155], v164 offset:2048
	ds_read_b128 v[156:159], v164 offset:3072
	ds_read_b128 v[160:163], v164 offset:16384
	ds_read_b128 v[168:171], v164 offset:17408
	ds_read_b128 v[172:175], v164 offset:18432
	ds_read_b128 v[176:179], v164 offset:19456
	v_lshl_add_u64 v[198:199], s[8:9], 0, v[140:141]
	s_add_i32 m0, s37, 0xc000
	ds_read_b128 v[180:183], v166
	ds_read_b128 v[184:187], v166 offset:1024
	ds_read_b128 v[188:191], v166 offset:2048
	ds_read_b128 v[192:195], v166 offset:3072
	ds_read_b128 v[202:205], v166 offset:4096
	ds_read_b128 v[206:209], v166 offset:5120
	ds_read_b128 v[210:213], v166 offset:6144
	ds_read_b128 v[214:217], v166 offset:7168
	global_load_lds_dwordx4 v[198:199], off
	s_add_i32 m0, s37, 0xe000
	v_lshl_add_u64 v[198:199], s[8:9], 0, v[142:143]
	global_load_lds_dwordx4 v[198:199], off
	s_waitcnt vmcnt(8) lgkmcnt(0)
	s_barrier
	s_setprio 1
	v_mfma_f32_16x16x32_bf16 v[128:131], v[144:147], v[180:183], 0
	v_mfma_f32_16x16x32_bf16 v[120:123], v[152:155], v[180:183], 0
	v_mfma_f32_16x16x32_bf16 v[112:115], v[144:147], v[188:191], 0
	v_mfma_f32_16x16x32_bf16 v[104:107], v[152:155], v[188:191], 0
	v_mfma_f32_16x16x32_bf16 v[96:99], v[144:147], v[202:205], 0
	v_mfma_f32_16x16x32_bf16 v[88:91], v[152:155], v[202:205], 0
	v_mfma_f32_16x16x32_bf16 v[80:83], v[144:147], v[210:213], 0
	v_mfma_f32_16x16x32_bf16 v[72:75], v[152:155], v[210:213], 0
	v_mfma_f32_16x16x32_bf16 v[128:131], v[148:151], v[184:187], v[128:131]
	v_mfma_f32_16x16x32_bf16 v[120:123], v[156:159], v[184:187], v[120:123]
	v_mfma_f32_16x16x32_bf16 v[112:115], v[148:151], v[192:195], v[112:115]
	v_mfma_f32_16x16x32_bf16 v[104:107], v[156:159], v[192:195], v[104:107]
	v_mfma_f32_16x16x32_bf16 v[96:99], v[148:151], v[206:209], v[96:99]
	v_mfma_f32_16x16x32_bf16 v[88:91], v[156:159], v[206:209], v[88:91]
	v_mfma_f32_16x16x32_bf16 v[80:83], v[148:151], v[214:217], v[80:83]
	v_mfma_f32_16x16x32_bf16 v[72:75], v[156:159], v[214:217], v[72:75]
	s_setprio 0
	s_setprio 1
	v_mfma_f32_16x16x32_bf16 v[124:127], v[160:163], v[180:183], 0
	v_mfma_f32_16x16x32_bf16 v[116:119], v[172:175], v[180:183], 0
	v_mfma_f32_16x16x32_bf16 v[108:111], v[160:163], v[188:191], 0
	v_mfma_f32_16x16x32_bf16 v[100:103], v[172:175], v[188:191], 0
	v_mfma_f32_16x16x32_bf16 v[92:95], v[160:163], v[202:205], 0
	v_mfma_f32_16x16x32_bf16 v[84:87], v[172:175], v[202:205], 0
	v_mfma_f32_16x16x32_bf16 v[76:79], v[160:163], v[210:213], 0
	v_mfma_f32_16x16x32_bf16 v[68:71], v[172:175], v[210:213], 0
	v_mfma_f32_16x16x32_bf16 v[124:127], v[168:171], v[184:187], v[124:127]
	v_mfma_f32_16x16x32_bf16 v[116:119], v[176:179], v[184:187], v[116:119]
	v_mfma_f32_16x16x32_bf16 v[108:111], v[168:171], v[192:195], v[108:111]
	v_mfma_f32_16x16x32_bf16 v[100:103], v[176:179], v[192:195], v[100:103]
	v_mfma_f32_16x16x32_bf16 v[92:95], v[168:171], v[206:209], v[92:95]
	v_mfma_f32_16x16x32_bf16 v[84:87], v[176:179], v[206:209], v[84:87]
	v_mfma_f32_16x16x32_bf16 v[76:79], v[168:171], v[214:217], v[76:79]
	v_mfma_f32_16x16x32_bf16 v[68:71], v[176:179], v[214:217], v[68:71]
	s_setprio 0
	s_barrier
	v_lshl_add_u64 v[198:199], s[24:25], 0, v[134:135]
	s_add_i32 m0, s35, 0x10000
	ds_read_b128 v[180:183], v166 offset:16384
	ds_read_b128 v[184:187], v166 offset:17408
	ds_read_b128 v[188:191], v166 offset:18432
	ds_read_b128 v[192:195], v166 offset:19456
	ds_read_b128 v[202:205], v166 offset:20480
	ds_read_b128 v[206:209], v166 offset:21504
	ds_read_b128 v[210:213], v166 offset:22528
	ds_read_b128 v[214:217], v166 offset:23552
	global_load_lds_dwordx4 v[198:199], off
	s_add_i32 m0, s35, 0x12000
	v_lshl_add_u64 v[218:219], s[24:25], 0, v[0:1]
	global_load_lds_dwordx4 v[218:219], off
	v_lshl_add_u64 v[220:221], v[198:199], 0, s[100:101]
	s_add_i32 m0, s35, 0x14000
	v_lshl_add_u64 v[222:223], s[26:27], 0, v[132:133]
	global_load_lds_dwordx4 v[220:221], off
	s_add_i32 m0, s35, 0x16000
	v_lshl_add_u64 v[220:221], v[218:219], 0, s[100:101]
	global_load_lds_dwordx4 v[220:221], off
	s_mov_b32 m0, s37
	v_lshl_add_u64 v[220:221], s[26:27], 0, v[136:137]
	global_load_lds_dwordx4 v[220:221], off
	s_mov_b32 m0, s38
	s_add_i32 s47, 0, 0x18000
	global_load_lds_dwordx4 v[222:223], off
	s_waitcnt vmcnt(8) lgkmcnt(0)
	s_barrier
; #define PG8_STAGE(bufoff, gbase, voff) do { _Pragma("unroll") for (int _i = 0; _i < 2; ++_i) \
;         __builtin_amdgcn_global_load_lds((const unsigned*)((const char*)(gbase) + (voff)[_i]), (PG8_LAS unsigned*)(lds + (bufoff) + ldsw + _i * 8192), 16, 0, 0); } while (0)
; #define PG8_LDA(dst, b, h) do { _Pragma("unroll") for (int m = 0; m < 4; ++m) _Pragma("unroll") for (int k = 0; k < 2; ++k) dst[m][k] = *(const PG8_LAS bf16x8*)(lds + PG8_SA(b, h) + aoff + m * 2048 + k * 1024); } while (0)
; #define PG8_LDB(dst, b, h) do { _Pragma("unroll") for (int n = 0; n < 2; ++n) _Pragma("unroll") for (int k = 0; k < 2; ++k) dst[n][k] = *(const PG8_LAS bf16x8*)(lds + PG8_SB(b, h) + boff + n * 2048 + k * 1024); } while (0)
; #define PG8_MMA(ai, bj, At, Bt) do { __builtin_amdgcn_s_setprio(1); _Pragma("unroll") for (int m = 0; m < 4; ++m) _Pragma("unroll") for (int n = 0; n < 2; ++n) _Pragma("unroll") for (int k = 0; k < 2; ++k) \
;         acc[ai][bj][m][n] = __builtin_amdgcn_mfma_f32_16x16x32_bf16(Bt[n][k], At[m][k], acc[ai][bj][m][n], 0, 0, 0); __builtin_amdgcn_s_setprio(0); } while (0)
; #define PG8_WAIT_V(n) asm volatile("s_waitcnt vmcnt(" #n ")" ::: "memory")
; #define PG8_WAIT_L(n) asm volatile("s_waitcnt lgkmcnt(" #n ")" ::: "memory")
; #define PG8_BAR __builtin_amdgcn_s_barrier()
; #define PG8_SCHED __builtin_amdgcn_sched_barrier(0)
; template <class Epi, class Sched, bool ALIGN_EPI = false, bool SP2 = false>
; __device__ __forceinline__ void gemm_phase(PG8_LAS unsigned char* lds, const Gemm g, const Sched& S, const Epi& E) {
;     ...
;             PG8_LDB(B0, 0, 0); PG8_LDB(B1, 0, 1); PG8_SCHED; PG8_LDA(At, 0, 0); PG8_STAGE(PG8_SA(1, 1), a1 + hstep, voffA);
;             PG8_WAIT_V(8); PG8_WAIT_L(0); PG8_BAR; PG8_MMA(0, 0, At, B0); PG8_MMA(0, 1, At, B1); PG8_BAR; PG8_SCHED;
;             PG8_LDA(At, 0, 1); PG8_STAGE(PG8_SB(0, 0), b2, voffB); PG8_STAGE(PG8_SB(0, 1), b2 + hstep, voffB); PG8_STAGE(PG8_SA(0, 0), a2, voffA);
;             PG8_WAIT_V(8); PG8_WAIT_L(0); PG8_BAR; PG8_MMA(1, 0, At, B0); PG8_MMA(1, 1, At, B1); PG8_BAR; PG8_SCHED;
	s_setprio 1
	v_mfma_f32_16x16x32_bf16 v[64:67], v[144:147], v[180:183], 0
	v_mfma_f32_16x16x32_bf16 v[56:59], v[152:155], v[180:183], 0
	v_mfma_f32_16x16x32_bf16 v[48:51], v[144:147], v[188:191], 0
	v_mfma_f32_16x16x32_bf16 v[40:43], v[152:155], v[188:191], 0
	v_mfma_f32_16x16x32_bf16 v[32:35], v[144:147], v[202:205], 0
	v_mfma_f32_16x16x32_bf16 v[24:27], v[152:155], v[202:205], 0
	v_mfma_f32_16x16x32_bf16 v[16:19], v[144:147], v[210:213], 0
	v_mfma_f32_16x16x32_bf16 v[8:11], v[152:155], v[210:213], 0
	v_mfma_f32_16x16x32_bf16 v[64:67], v[148:151], v[184:187], v[64:67]
	v_mfma_f32_16x16x32_bf16 v[56:59], v[156:159], v[184:187], v[56:59]
	v_mfma_f32_16x16x32_bf16 v[48:51], v[148:151], v[192:195], v[48:51]
	v_mfma_f32_16x16x32_bf16 v[40:43], v[156:159], v[192:195], v[40:43]
	v_mfma_f32_16x16x32_bf16 v[32:35], v[148:151], v[206:209], v[32:35]
	v_mfma_f32_16x16x32_bf16 v[24:27], v[156:159], v[206:209], v[24:27]
	v_mfma_f32_16x16x32_bf16 v[16:19], v[148:151], v[214:217], v[16:19]
	v_mfma_f32_16x16x32_bf16 v[8:11], v[156:159], v[214:217], v[8:11]
	s_setprio 0
	s_setprio 1
	v_mfma_f32_16x16x32_bf16 v[60:63], v[160:163], v[180:183], 0
	v_mfma_f32_16x16x32_bf16 v[52:55], v[172:175], v[180:183], 0
	v_mfma_f32_16x16x32_bf16 v[44:47], v[160:163], v[188:191], 0
	v_mfma_f32_16x16x32_bf16 v[36:39], v[172:175], v[188:191], 0
	v_mfma_f32_16x16x32_bf16 v[28:31], v[160:163], v[202:205], 0
	v_mfma_f32_16x16x32_bf16 v[20:23], v[172:175], v[202:205], 0
	v_mfma_f32_16x16x32_bf16 v[12:15], v[160:163], v[210:213], 0
	v_mfma_f32_16x16x32_bf16 v[4:7], v[172:175], v[210:213], 0
	v_mfma_f32_16x16x32_bf16 v[60:63], v[168:171], v[184:187], v[60:63]
	v_mfma_f32_16x16x32_bf16 v[52:55], v[176:179], v[184:187], v[52:55]
	v_mfma_f32_16x16x32_bf16 v[44:47], v[168:171], v[192:195], v[44:47]
	v_mfma_f32_16x16x32_bf16 v[36:39], v[176:179], v[192:195], v[36:39]
	v_mfma_f32_16x16x32_bf16 v[28:31], v[168:171], v[206:209], v[28:31]
	v_mfma_f32_16x16x32_bf16 v[20:23], v[176:179], v[206:209], v[20:23]
	v_mfma_f32_16x16x32_bf16 v[12:15], v[168:171], v[214:217], v[12:15]
	v_mfma_f32_16x16x32_bf16 v[4:7], v[176:179], v[214:217], v[4:7]
	s_setprio 0
	s_barrier
	s_branch .Lkmid_2
.LBB0_405:
	s_add_u32 s24, s8, 0xfffc0080
	s_addc_u32 s25, s9, -1
	s_cmp_eq_u32 s46, 12
	s_cselect_b32 s27, s7, s25
	s_cselect_b32 s26, s17, s24
	s_cselect_b32 s25, s19, s45
	s_cselect_b32 s24, s43, s44
	s_add_i32 s50, 0, 0x14000
	ds_read_b128 v[144:147], v164
	ds_read_b128 v[148:151], v164 offset:1024
	ds_read_b128 v[152:155], v164 offset:2048
	ds_read_b128 v[156:159], v164 offset:3072
	ds_read_b128 v[160:163], v164 offset:16384
	ds_read_b128 v[168:171], v164 offset:17408
	ds_read_b128 v[172:175], v164 offset:18432
	ds_read_b128 v[176:179], v164 offset:19456
	v_lshl_add_u64 v[198:199], s[8:9], 0, v[140:141]
	s_add_i32 m0, s37, 0xc000
	ds_read_b128 v[180:183], v166
	ds_read_b128 v[184:187], v166 offset:1024
	ds_read_b128 v[188:191], v166 offset:2048
	ds_read_b128 v[192:195], v166 offset:3072
	ds_read_b128 v[202:205], v166 offset:4096
	ds_read_b128 v[206:209], v166 offset:5120
	ds_read_b128 v[210:213], v166 offset:6144
	ds_read_b128 v[214:217], v166 offset:7168
	global_load_lds_dwordx4 v[198:199], off
	s_add_i32 m0, s37, 0xe000
	v_lshl_add_u64 v[198:199], s[8:9], 0, v[142:143]
	global_load_lds_dwordx4 v[198:199], off
	s_waitcnt vmcnt(8) lgkmcnt(0)
	s_barrier
	s_setprio 1
	v_mfma_f32_16x16x32_bf16 v[128:131], v[144:147], v[180:183], v[128:131]
	v_mfma_f32_16x16x32_bf16 v[120:123], v[152:155], v[180:183], v[120:123]
	v_mfma_f32_16x16x32_bf16 v[112:115], v[144:147], v[188:191], v[112:115]
	v_mfma_f32_16x16x32_bf16 v[104:107], v[152:155], v[188:191], v[104:107]
	v_mfma_f32_16x16x32_bf16 v[96:99], v[144:147], v[202:205], v[96:99]
	v_mfma_f32_16x16x32_bf16 v[88:91], v[152:155], v[202:205], v[88:91]
	v_mfma_f32_16x16x32_bf16 v[80:83], v[144:147], v[210:213], v[80:83]
	v_mfma_f32_16x16x32_bf16 v[72:75], v[152:155], v[210:213], v[72:75]
	v_mfma_f32_16x16x32_bf16 v[128:131], v[148:151], v[184:187], v[128:131]
	v_mfma_f32_16x16x32_bf16 v[120:123], v[156:159], v[184:187], v[120:123]
	v_mfma_f32_16x16x32_bf16 v[112:115], v[148:151], v[192:195], v[112:115]
	v_mfma_f32_16x16x32_bf16 v[104:107], v[156:159], v[192:195], v[104:107]
	v_mfma_f32_16x16x32_bf16 v[96:99], v[148:151], v[206:209], v[96:99]
	v_mfma_f32_16x16x32_bf16 v[88:91], v[156:159], v[206:209], v[88:91]
	v_mfma_f32_16x16x32_bf16 v[80:83], v[148:151], v[214:217], v[80:83]
	v_mfma_f32_16x16x32_bf16 v[72:75], v[156:159], v[214:217], v[72:75]
	s_setprio 0
	s_setprio 1
	v_mfma_f32_16x16x32_bf16 v[124:127], v[160:163], v[180:183], v[124:127]
	v_mfma_f32_16x16x32_bf16 v[116:119], v[172:175], v[180:183], v[116:119]
	v_mfma_f32_16x16x32_bf16 v[108:111], v[160:163], v[188:191], v[108:111]
	v_mfma_f32_16x16x32_bf16 v[100:103], v[172:175], v[188:191], v[100:103]
	v_mfma_f32_16x16x32_bf16 v[92:95], v[160:163], v[202:205], v[92:95]
	v_mfma_f32_16x16x32_bf16 v[84:87], v[172:175], v[202:205], v[84:87]
	v_mfma_f32_16x16x32_bf16 v[76:79], v[160:163], v[210:213], v[76:79]
	v_mfma_f32_16x16x32_bf16 v[68:71], v[172:175], v[210:213], v[68:71]
	v_mfma_f32_16x16x32_bf16 v[124:127], v[168:171], v[184:187], v[124:127]
	v_mfma_f32_16x16x32_bf16 v[116:119], v[176:179], v[184:187], v[116:119]
	v_mfma_f32_16x16x32_bf16 v[108:111], v[168:171], v[192:195], v[108:111]
	v_mfma_f32_16x16x32_bf16 v[100:103], v[176:179], v[192:195], v[100:103]
	v_mfma_f32_16x16x32_bf16 v[92:95], v[168:171], v[206:209], v[92:95]
	v_mfma_f32_16x16x32_bf16 v[84:87], v[176:179], v[206:209], v[84:87]
	v_mfma_f32_16x16x32_bf16 v[76:79], v[168:171], v[214:217], v[76:79]
	v_mfma_f32_16x16x32_bf16 v[68:71], v[176:179], v[214:217], v[68:71]
	s_setprio 0
	s_barrier
; #define PG8_STAGE(bufoff, gbase, voff) do { _Pragma("unroll") for (int _i = 0; _i < 2; ++_i) \
;         __builtin_amdgcn_global_load_lds((const unsigned*)((const char*)(gbase) + (voff)[_i]), (PG8_LAS unsigned*)(lds + (bufoff) + ldsw + _i * 8192), 16, 0, 0); } while (0)
; #define PG8_LDA(dst, b, h) do { _Pragma("unroll") for (int m = 0; m < 4; ++m) _Pragma("unroll") for (int k = 0; k < 2; ++k) dst[m][k] = *(const PG8_LAS bf16x8*)(lds + PG8_SA(b, h) + aoff + m * 2048 + k * 1024); } while (0)
; #define PG8_MMA(ai, bj, At, Bt) do { __builtin_amdgcn_s_setprio(1); _Pragma("unroll") for (int m = 0; m < 4; ++m) _Pragma("unroll") for (int n = 0; n < 2; ++n) _Pragma("unroll") for (int k = 0; k < 2; ++k) \
;         acc[ai][bj][m][n] = __builtin_amdgcn_mfma_f32_16x16x32_bf16(Bt[n][k], At[m][k], acc[ai][bj][m][n], 0, 0, 0); __builtin_amdgcn_s_setprio(0); } while (0)
; #define PG8_WAIT_V(n) asm volatile("s_waitcnt vmcnt(" #n ")" ::: "memory")
; #define PG8_WAIT_L(n) asm volatile("s_waitcnt lgkmcnt(" #n ")" ::: "memory")
; #define PG8_BAR __builtin_amdgcn_s_barrier()
; #define PG8_SCHED __builtin_amdgcn_sched_barrier(0)
; template <class Epi, class Sched, bool ALIGN_EPI = false, bool SP2 = false>
; __device__ __forceinline__ void gemm_phase(PG8_LAS unsigned char* lds, const Gemm g, const Sched& S, const Epi& E) {
;     ...
;             PG8_LDA(At, 0, 1); PG8_STAGE(PG8_SB(0, 0), b2, voffB); PG8_STAGE(PG8_SB(0, 1), b2 + hstep, voffB); PG8_STAGE(PG8_SA(0, 0), a2, voffA);
;             PG8_WAIT_V(8); PG8_WAIT_L(0); PG8_BAR; PG8_MMA(1, 0, At, B0); PG8_MMA(1, 1, At, B1); PG8_BAR; PG8_SCHED;
	v_lshl_add_u64 v[198:199], s[24:25], 0, v[134:135]
	s_add_i32 m0, s35, 0x10000
	ds_read_b128 v[180:183], v166 offset:16384
	ds_read_b128 v[184:187], v166 offset:17408
	ds_read_b128 v[188:191], v166 offset:18432
	ds_read_b128 v[192:195], v166 offset:19456
	ds_read_b128 v[202:205], v166 offset:20480
	ds_read_b128 v[206:209], v166 offset:21504
	ds_read_b128 v[210:213], v166 offset:22528
	ds_read_b128 v[214:217], v166 offset:23552
	global_load_lds_dwordx4 v[198:199], off
	s_add_i32 m0, s35, 0x12000
	v_lshl_add_u64 v[218:219], s[24:25], 0, v[0:1]
	global_load_lds_dwordx4 v[218:219], off
	v_lshl_add_u64 v[220:221], v[198:199], 0, s[100:101]
	s_add_i32 m0, s35, 0x14000
	v_lshl_add_u64 v[222:223], s[26:27], 0, v[132:133]
	global_load_lds_dwordx4 v[220:221], off
	s_add_i32 m0, s35, 0x16000
	v_lshl_add_u64 v[220:221], v[218:219], 0, s[100:101]
	global_load_lds_dwordx4 v[220:221], off
	s_mov_b32 m0, s37
	v_lshl_add_u64 v[220:221], s[26:27], 0, v[136:137]
	global_load_lds_dwordx4 v[220:221], off
	s_mov_b32 m0, s38
	s_add_i32 s47, 0, 0x18000
	global_load_lds_dwordx4 v[222:223], off
	s_waitcnt vmcnt(8) lgkmcnt(0)
	s_barrier
	s_setprio 1
	v_mfma_f32_16x16x32_bf16 v[64:67], v[144:147], v[180:183], v[64:67]
	v_mfma_f32_16x16x32_bf16 v[56:59], v[152:155], v[180:183], v[56:59]
	v_mfma_f32_16x16x32_bf16 v[48:51], v[144:147], v[188:191], v[48:51]
	v_mfma_f32_16x16x32_bf16 v[40:43], v[152:155], v[188:191], v[40:43]
	v_mfma_f32_16x16x32_bf16 v[32:35], v[144:147], v[202:205], v[32:35]
	v_mfma_f32_16x16x32_bf16 v[24:27], v[152:155], v[202:205], v[24:27]
	v_mfma_f32_16x16x32_bf16 v[16:19], v[144:147], v[210:213], v[16:19]
	v_mfma_f32_16x16x32_bf16 v[8:11], v[152:155], v[210:213], v[8:11]
	v_mfma_f32_16x16x32_bf16 v[64:67], v[148:151], v[184:187], v[64:67]
	v_mfma_f32_16x16x32_bf16 v[56:59], v[156:159], v[184:187], v[56:59]
	v_mfma_f32_16x16x32_bf16 v[48:51], v[148:151], v[192:195], v[48:51]
	v_mfma_f32_16x16x32_bf16 v[40:43], v[156:159], v[192:195], v[40:43]
	v_mfma_f32_16x16x32_bf16 v[32:35], v[148:151], v[206:209], v[32:35]
	v_mfma_f32_16x16x32_bf16 v[24:27], v[156:159], v[206:209], v[24:27]
	v_mfma_f32_16x16x32_bf16 v[16:19], v[148:151], v[214:217], v[16:19]
	v_mfma_f32_16x16x32_bf16 v[8:11], v[156:159], v[214:217], v[8:11]
	s_setprio 0
	s_setprio 1
	v_mfma_f32_16x16x32_bf16 v[60:63], v[160:163], v[180:183], v[60:63]
	v_mfma_f32_16x16x32_bf16 v[52:55], v[172:175], v[180:183], v[52:55]
	v_mfma_f32_16x16x32_bf16 v[44:47], v[160:163], v[188:191], v[44:47]
	v_mfma_f32_16x16x32_bf16 v[36:39], v[172:175], v[188:191], v[36:39]
	v_mfma_f32_16x16x32_bf16 v[28:31], v[160:163], v[202:205], v[28:31]
	v_mfma_f32_16x16x32_bf16 v[20:23], v[172:175], v[202:205], v[20:23]
	v_mfma_f32_16x16x32_bf16 v[12:15], v[160:163], v[210:213], v[12:15]
	v_mfma_f32_16x16x32_bf16 v[4:7], v[172:175], v[210:213], v[4:7]
	v_mfma_f32_16x16x32_bf16 v[60:63], v[168:171], v[184:187], v[60:63]
	v_mfma_f32_16x16x32_bf16 v[52:55], v[176:179], v[184:187], v[52:55]
	v_mfma_f32_16x16x32_bf16 v[44:47], v[168:171], v[192:195], v[44:47]
	v_mfma_f32_16x16x32_bf16 v[36:39], v[176:179], v[192:195], v[36:39]
	v_mfma_f32_16x16x32_bf16 v[28:31], v[168:171], v[206:209], v[28:31]
	v_mfma_f32_16x16x32_bf16 v[20:23], v[176:179], v[206:209], v[20:23]
	v_mfma_f32_16x16x32_bf16 v[12:15], v[168:171], v[214:217], v[12:15]
	v_mfma_f32_16x16x32_bf16 v[4:7], v[176:179], v[214:217], v[4:7]
	s_setprio 0
	s_barrier
; #define PG8_STAGE(bufoff, gbase, voff) do { _Pragma("unroll") for (int _i = 0; _i < 2; ++_i) \
;         __builtin_amdgcn_global_load_lds((const unsigned*)((const char*)(gbase) + (voff)[_i]), (PG8_LAS unsigned*)(lds + (bufoff) + ldsw + _i * 8192), 16, 0, 0); } while (0)
; #define PG8_LDA(dst, b, h) do { _Pragma("unroll") for (int m = 0; m < 4; ++m) _Pragma("unroll") for (int k = 0; k < 2; ++k) dst[m][k] = *(const PG8_LAS bf16x8*)(lds + PG8_SA(b, h) + aoff + m * 2048 + k * 1024); } while (0)
; #define PG8_LDB(dst, b, h) do { _Pragma("unroll") for (int n = 0; n < 2; ++n) _Pragma("unroll") for (int k = 0; k < 2; ++k) dst[n][k] = *(const PG8_LAS bf16x8*)(lds + PG8_SB(b, h) + boff + n * 2048 + k * 1024); } while (0)
; template <class Epi, class Sched, bool ALIGN_EPI = false, bool SP2 = false>
; __device__ __forceinline__ void gemm_phase(PG8_LAS unsigned char* lds, const Gemm g, const Sched& S, const Epi& E) {
;     ...
;         for (int t = 0; t < nt; t += 2) {
;             const bool last = (t == nt - 2);
;             const char* a1 = cA + (size_t)(t + 1) * kstep;
;             const char* a2 = last ? nA : cA + (size_t)(t + 2) * kstep; const char* b2 = last ? nB : cB + (size_t)(t + 2) * kstep;
;             const char* a3 = a2 + kstep; const char* b3 = b2 + kstep;
;             if (last && has_next) S.a_ready(nxt);
;             if constexpr (SP2) {
;             PG8_LDB(B0, 0, 0); PG8_LDB(B1, 0, 1); PG8_SCHED; PG8_LDA(At, 0, 0); PG8_STAGE(PG8_SA(1, 1), a1 + hstep, voffA);
;             PG8_WAIT_V(8); PG8_WAIT_L(0); PG8_BAR; PG8_MMA(0, 0, At, B0); PG8_MMA(0, 1, At, B1); PG8_BAR; PG8_SCHED;
;             PG8_LDA(At, 0, 1); PG8_STAGE(PG8_SB(0, 0), b2, voffB); PG8_STAGE(PG8_SB(0, 1), b2 + hstep, voffB); PG8_STAGE(PG8_SA(0, 0), a2, voffA);
;             PG8_WAIT_V(8); PG8_WAIT_L(0); PG8_BAR; PG8_MMA(1, 0, At, B0); PG8_MMA(1, 1, At, B1); PG8_BAR; PG8_SCHED;
;             PG8_LDB(B0, 1, 0); PG8_LDB(B1, 1, 1); PG8_SCHED; PG8_LDA(At, 1, 0); PG8_STAGE(PG8_SA(0, 1), a2 + hstep, voffA);
;             PG8_WAIT_V(8); PG8_WAIT_L(0); PG8_BAR; PG8_MMA(0, 0, At, B0); PG8_MMA(0, 1, At, B1); PG8_BAR; PG8_SCHED;
;             PG8_LDA(At, 1, 1); PG8_STAGE(PG8_SB(1, 0), b3, voffB); PG8_STAGE(PG8_SB(1, 1), b3 + hstep, voffB); PG8_STAGE(PG8_SA(1, 0), a3, voffA);
;             PG8_WAIT_V(8); PG8_WAIT_L(0); PG8_BAR; PG8_MMA(1, 0, At, B0); PG8_MMA(1, 1, At, B1); PG8_BAR; PG8_SCHED;
.Lkmid_2:
	ds_read_b128 v[144:147], v164 offset:32768
	ds_read_b128 v[148:151], v164 offset:33792
	ds_read_b128 v[152:155], v164 offset:34816
	ds_read_b128 v[156:159], v164 offset:35840
	ds_read_b128 v[160:163], v164 offset:49152
	ds_read_b128 v[168:171], v164 offset:50176
	ds_read_b128 v[172:175], v164 offset:51200
	ds_read_b128 v[176:179], v164 offset:52224
	s_mov_b32 m0, s39
	v_lshl_add_u64 v[224:225], v[220:221], 0, s[100:101]
	ds_read_b128 v[180:183], v166 offset:32768
	ds_read_b128 v[184:187], v166 offset:33792
	ds_read_b128 v[188:191], v166 offset:34816
	ds_read_b128 v[192:195], v166 offset:35840
	ds_read_b128 v[202:205], v166 offset:36864
	ds_read_b128 v[206:209], v166 offset:37888
	ds_read_b128 v[210:213], v166 offset:38912
	ds_read_b128 v[214:217], v166 offset:39936
	global_load_lds_dwordx4 v[224:225], off
	s_mov_b32 m0, s40
	v_lshl_add_u64 v[224:225], v[222:223], 0, s[100:101]
	global_load_lds_dwordx4 v[224:225], off
	s_waitcnt vmcnt(8) lgkmcnt(0)
	s_barrier
	s_setprio 1
	v_mfma_f32_16x16x32_bf16 v[128:131], v[144:147], v[180:183], v[128:131]
	v_mfma_f32_16x16x32_bf16 v[120:123], v[152:155], v[180:183], v[120:123]
	v_mfma_f32_16x16x32_bf16 v[112:115], v[144:147], v[188:191], v[112:115]
	v_mfma_f32_16x16x32_bf16 v[104:107], v[152:155], v[188:191], v[104:107]
	v_mfma_f32_16x16x32_bf16 v[96:99], v[144:147], v[202:205], v[96:99]
	v_mfma_f32_16x16x32_bf16 v[88:91], v[152:155], v[202:205], v[88:91]
	v_mfma_f32_16x16x32_bf16 v[80:83], v[144:147], v[210:213], v[80:83]
	v_mfma_f32_16x16x32_bf16 v[72:75], v[152:155], v[210:213], v[72:75]
	v_mfma_f32_16x16x32_bf16 v[128:131], v[148:151], v[184:187], v[128:131]
	v_mfma_f32_16x16x32_bf16 v[120:123], v[156:159], v[184:187], v[120:123]
	v_mfma_f32_16x16x32_bf16 v[112:115], v[148:151], v[192:195], v[112:115]
	v_mfma_f32_16x16x32_bf16 v[104:107], v[156:159], v[192:195], v[104:107]
	v_mfma_f32_16x16x32_bf16 v[96:99], v[148:151], v[206:209], v[96:99]
	v_mfma_f32_16x16x32_bf16 v[88:91], v[156:159], v[206:209], v[88:91]
	v_mfma_f32_16x16x32_bf16 v[80:83], v[148:151], v[214:217], v[80:83]
	v_mfma_f32_16x16x32_bf16 v[72:75], v[156:159], v[214:217], v[72:75]
	s_setprio 0
	s_setprio 1
	v_mfma_f32_16x16x32_bf16 v[124:127], v[160:163], v[180:183], v[124:127]
	v_mfma_f32_16x16x32_bf16 v[116:119], v[172:175], v[180:183], v[116:119]
	v_mfma_f32_16x16x32_bf16 v[108:111], v[160:163], v[188:191], v[108:111]
	v_mfma_f32_16x16x32_bf16 v[100:103], v[172:175], v[188:191], v[100:103]
	v_mfma_f32_16x16x32_bf16 v[92:95], v[160:163], v[202:205], v[92:95]
	v_mfma_f32_16x16x32_bf16 v[84:87], v[172:175], v[202:205], v[84:87]
	v_mfma_f32_16x16x32_bf16 v[76:79], v[160:163], v[210:213], v[76:79]
	v_mfma_f32_16x16x32_bf16 v[68:71], v[172:175], v[210:213], v[68:71]
	v_mfma_f32_16x16x32_bf16 v[124:127], v[168:171], v[184:187], v[124:127]
	v_mfma_f32_16x16x32_bf16 v[116:119], v[176:179], v[184:187], v[116:119]
	v_mfma_f32_16x16x32_bf16 v[108:111], v[168:171], v[192:195], v[108:111]
	v_mfma_f32_16x16x32_bf16 v[100:103], v[176:179], v[192:195], v[100:103]
	v_mfma_f32_16x16x32_bf16 v[92:95], v[168:171], v[206:209], v[92:95]
	v_mfma_f32_16x16x32_bf16 v[84:87], v[176:179], v[206:209], v[84:87]
	v_mfma_f32_16x16x32_bf16 v[76:79], v[168:171], v[214:217], v[76:79]
	v_mfma_f32_16x16x32_bf16 v[68:71], v[176:179], v[214:217], v[68:71]
	s_setprio 0
	s_barrier
	s_add_i32 m0, s35, 0x17f80
	ds_read_b128 v[180:183], v166 offset:49152
	ds_read_b128 v[184:187], v166 offset:50176
	ds_read_b128 v[188:191], v166 offset:51200
	ds_read_b128 v[192:195], v166 offset:52224
	ds_read_b128 v[202:205], v166 offset:53248
	ds_read_b128 v[206:209], v166 offset:54272
	ds_read_b128 v[210:213], v166 offset:55296
	ds_read_b128 v[214:217], v166 offset:56320
	global_load_lds_dwordx4 v[198:199], off offset:128
	s_add_i32 m0, s35, 0x19f80
	v_lshl_add_u64 v[198:199], v[198:199], 0, s[100:101]
	global_load_lds_dwordx4 v[218:219], off offset:128
	s_add_i32 m0, s35, 0x1bf80
	v_lshl_add_u64 v[224:225], v[218:219], 0, s[100:101]
	global_load_lds_dwordx4 v[198:199], off offset:128
	s_add_i32 m0, s35, 0x1df80
	s_add_i32 s46, s46, 2
	global_load_lds_dwordx4 v[224:225], off offset:128
	s_add_i32 m0, s41, 0xffffff80
	s_add_u32 s8, s8, 0x100
	s_addc_u32 s9, s9, 0
	global_load_lds_dwordx4 v[220:221], off offset:128
	s_add_i32 m0, s42, 0xffffff80
	s_add_u32 s44, s44, 0x100
	s_addc_u32 s45, s45, 0
	global_load_lds_dwordx4 v[222:223], off offset:128
	s_waitcnt vmcnt(8) lgkmcnt(0)
	s_barrier
	s_setprio 1
	v_mfma_f32_16x16x32_bf16 v[64:67], v[144:147], v[180:183], v[64:67]
	v_mfma_f32_16x16x32_bf16 v[56:59], v[152:155], v[180:183], v[56:59]
	v_mfma_f32_16x16x32_bf16 v[48:51], v[144:147], v[188:191], v[48:51]
	v_mfma_f32_16x16x32_bf16 v[40:43], v[152:155], v[188:191], v[40:43]
	v_mfma_f32_16x16x32_bf16 v[32:35], v[144:147], v[202:205], v[32:35]
	v_mfma_f32_16x16x32_bf16 v[24:27], v[152:155], v[202:205], v[24:27]
	v_mfma_f32_16x16x32_bf16 v[16:19], v[144:147], v[210:213], v[16:19]
	v_mfma_f32_16x16x32_bf16 v[8:11], v[152:155], v[210:213], v[8:11]
	v_mfma_f32_16x16x32_bf16 v[64:67], v[148:151], v[184:187], v[64:67]
	v_mfma_f32_16x16x32_bf16 v[56:59], v[156:159], v[184:187], v[56:59]
	v_mfma_f32_16x16x32_bf16 v[48:51], v[148:151], v[192:195], v[48:51]
	v_mfma_f32_16x16x32_bf16 v[40:43], v[156:159], v[192:195], v[40:43]
	v_mfma_f32_16x16x32_bf16 v[32:35], v[148:151], v[206:209], v[32:35]
	v_mfma_f32_16x16x32_bf16 v[24:27], v[156:159], v[206:209], v[24:27]
	v_mfma_f32_16x16x32_bf16 v[16:19], v[148:151], v[214:217], v[16:19]
	v_mfma_f32_16x16x32_bf16 v[8:11], v[156:159], v[214:217], v[8:11]
	s_setprio 0
	s_setprio 1
	v_mfma_f32_16x16x32_bf16 v[60:63], v[160:163], v[180:183], v[60:63]
	v_mfma_f32_16x16x32_bf16 v[52:55], v[172:175], v[180:183], v[52:55]
	v_mfma_f32_16x16x32_bf16 v[44:47], v[160:163], v[188:191], v[44:47]
	v_mfma_f32_16x16x32_bf16 v[36:39], v[172:175], v[188:191], v[36:39]
	v_mfma_f32_16x16x32_bf16 v[28:31], v[160:163], v[202:205], v[28:31]
	v_mfma_f32_16x16x32_bf16 v[20:23], v[172:175], v[202:205], v[20:23]
	v_mfma_f32_16x16x32_bf16 v[12:15], v[160:163], v[210:213], v[12:15]
	v_mfma_f32_16x16x32_bf16 v[4:7], v[172:175], v[210:213], v[4:7]
	v_mfma_f32_16x16x32_bf16 v[60:63], v[168:171], v[184:187], v[60:63]
	v_mfma_f32_16x16x32_bf16 v[52:55], v[176:179], v[184:187], v[52:55]
	v_mfma_f32_16x16x32_bf16 v[44:47], v[168:171], v[192:195], v[44:47]
	v_mfma_f32_16x16x32_bf16 v[36:39], v[176:179], v[192:195], v[36:39]
	v_mfma_f32_16x16x32_bf16 v[28:31], v[168:171], v[206:209], v[28:31]
	v_mfma_f32_16x16x32_bf16 v[20:23], v[176:179], v[206:209], v[20:23]
	v_mfma_f32_16x16x32_bf16 v[12:15], v[168:171], v[214:217], v[12:15]
	v_mfma_f32_16x16x32_bf16 v[4:7], v[176:179], v[214:217], v[4:7]
	s_setprio 0
	s_barrier
	s_cmp_gt_u32 s46, 13
	s_cbranch_scc0 .LBB0_405
	s_and_b64 vcc, exec, s[14:15]
	s_cbranch_vccz .LBB0_408
	s_barrier

; #define PG8_STAGE(bufoff, gbase, voff) do { _Pragma("unroll") for (int _i = 0; _i < 2; ++_i) \
;         __builtin_amdgcn_global_load_lds((const unsigned*)((const char*)(gbase) + (voff)[_i]), (PG8_LAS unsigned*)(lds + (bufoff) + ldsw + _i * 8192), 16, 0, 0); } while (0)
; #define PG8_LDA(dst, b, h) do { _Pragma("unroll") for (int m = 0; m < 4; ++m) _Pragma("unroll") for (int k = 0; k < 2; ++k) dst[m][k] = *(const PG8_LAS bf16x8*)(lds + PG8_SA(b, h) + aoff + m * 2048 + k * 1024); } while (0)
; #define PG8_LDB(dst, b, h) do { _Pragma("unroll") for (int n = 0; n < 2; ++n) _Pragma("unroll") for (int k = 0; k < 2; ++k) dst[n][k] = *(const PG8_LAS bf16x8*)(lds + PG8_SB(b, h) + boff + n * 2048 + k * 1024); } while (0)
; #define PG8_MMA(ai, bj, At, Bt) do { __builtin_amdgcn_s_setprio(1); _Pragma("unroll") for (int m = 0; m < 4; ++m) _Pragma("unroll") for (int n = 0; n < 2; ++n) _Pragma("unroll") for (int k = 0; k < 2; ++k) \
;         acc[ai][bj][m][n] = __builtin_amdgcn_mfma_f32_16x16x32_bf16(Bt[n][k], At[m][k], acc[ai][bj][m][n], 0, 0, 0); __builtin_amdgcn_s_setprio(0); } while (0)
; #define PG8_WAIT_V(n) asm volatile("s_waitcnt vmcnt(" #n ")" ::: "memory")
; #define PG8_BAR __builtin_amdgcn_s_barrier()
; template <class Epi, class Sched, bool ALIGN_EPI = false, bool SP2 = false>
; __device__ __forceinline__ void gemm_phase(PG8_LAS unsigned char* lds, const Gemm g, const Sched& S, const Epi& E) {
;     ...
;         for (int t = 0; t < nt; t += 2) {
;             const bool last = (t == nt - 2);
;             const char* a1 = cA + (size_t)(t + 1) * kstep;
;             const char* a2 = last ? nA : cA + (size_t)(t + 2) * kstep; const char* b2 = last ? nB : cB + (size_t)(t + 2) * kstep;
;             const char* a3 = a2 + kstep; const char* b3 = b2 + kstep;
;             if (last && has_next) S.a_ready(nxt);
;             if constexpr (SP2) {
;             PG8_LDB(B0, 0, 0); PG8_LDB(B1, 0, 1); PG8_SCHED; PG8_LDA(At, 0, 0); PG8_STAGE(PG8_SA(1, 1), a1 + hstep, voffA);
;             PG8_WAIT_V(8); PG8_WAIT_L(0); PG8_BAR; PG8_MMA(0, 0, At, B0); PG8_MMA(0, 1, At, B1); PG8_BAR; PG8_SCHED;
;             PG8_LDA(At, 0, 1); PG8_STAGE(PG8_SB(0, 0), b2, voffB); PG8_STAGE(PG8_SB(0, 1), b2 + hstep, voffB); PG8_STAGE(PG8_SA(0, 0), a2, voffA);
;             PG8_WAIT_V(8); PG8_WAIT_L(0); PG8_BAR; PG8_MMA(1, 0, At, B0); PG8_MMA(1, 1, At, B1); PG8_BAR; PG8_SCHED;
.LBB0_479:
	s_mov_b32 s100, 0xb0000
	s_mov_b32 s101, 0
	s_add_u32 s44, s28, 0x100
	s_addc_u32 s45, s29, 0
	s_mov_b32 s53, -2
	s_add_u32 s8, s26, 0x100
	s_addc_u32 s9, s27, 0
	s_cmp_eq_u32 s53, 40
	s_cselect_b32 s31, s23, s9
	s_cselect_b32 s30, s22, s8
	s_cselect_b32 s29, s25, s45
	s_cselect_b32 s28, s24, s44
	ds_read_b128 v[68:71], v234
	ds_read_b128 v[80:83], v234 offset:1024
	ds_read_b128 v[92:95], v234 offset:2048
	ds_read_b128 v[100:103], v234 offset:3072
	ds_read_b128 v[112:115], v234 offset:16384
	ds_read_b128 v[120:123], v234 offset:17408
	ds_read_b128 v[132:135], v234 offset:18432
	ds_read_b128 v[144:147], v234 offset:19456
	v_lshl_add_u64 v[198:199], s[26:27], 0, v[204:205]
	s_add_i32 m0, s40, 0xc000
	ds_read_b128 v[156:159], v236
	ds_read_b128 v[168:171], v236 offset:1024
	ds_read_b128 v[172:175], v236 offset:2048
	ds_read_b128 v[176:179], v236 offset:3072
	ds_read_b128 v[180:183], v236 offset:4096
	ds_read_b128 v[184:187], v236 offset:5120
	ds_read_b128 v[188:191], v236 offset:6144
	ds_read_b128 v[208:211], v236 offset:7168
	global_load_lds_dwordx4 v[198:199], off
	s_add_i32 m0, s40, 0xe000
	v_lshl_add_u64 v[198:199], s[26:27], 0, v[206:207]
	global_load_lds_dwordx4 v[198:199], off
	s_waitcnt vmcnt(8) lgkmcnt(0)
	s_barrier
	s_setprio 1
	v_mfma_f32_16x16x32_bf16 v[164:167], v[68:71], v[156:159], 0
	v_mfma_f32_16x16x32_bf16 v[160:163], v[92:95], v[156:159], 0
	v_mfma_f32_16x16x32_bf16 v[140:143], v[68:71], v[172:175], 0
	v_mfma_f32_16x16x32_bf16 v[136:139], v[92:95], v[172:175], 0
	v_mfma_f32_16x16x32_bf16 v[116:119], v[68:71], v[180:183], 0
	v_mfma_f32_16x16x32_bf16 v[108:111], v[92:95], v[180:183], 0
	v_mfma_f32_16x16x32_bf16 v[88:91], v[68:71], v[188:191], 0
	v_mfma_f32_16x16x32_bf16 v[84:87], v[92:95], v[188:191], 0
	v_mfma_f32_16x16x32_bf16 v[164:167], v[80:83], v[168:171], v[164:167]
	v_mfma_f32_16x16x32_bf16 v[160:163], v[100:103], v[168:171], v[160:163]
	v_mfma_f32_16x16x32_bf16 v[140:143], v[80:83], v[176:179], v[140:143]
	v_mfma_f32_16x16x32_bf16 v[136:139], v[100:103], v[176:179], v[136:139]
	v_mfma_f32_16x16x32_bf16 v[116:119], v[80:83], v[184:187], v[116:119]
	v_mfma_f32_16x16x32_bf16 v[108:111], v[100:103], v[184:187], v[108:111]
	v_mfma_f32_16x16x32_bf16 v[88:91], v[80:83], v[208:211], v[88:91]
	v_mfma_f32_16x16x32_bf16 v[84:87], v[100:103], v[208:211], v[84:87]
	s_setprio 0
	s_setprio 1
	v_mfma_f32_16x16x32_bf16 v[152:155], v[112:115], v[156:159], 0
	v_mfma_f32_16x16x32_bf16 v[148:151], v[132:135], v[156:159], 0
	v_mfma_f32_16x16x32_bf16 v[128:131], v[112:115], v[172:175], 0
	v_mfma_f32_16x16x32_bf16 v[124:127], v[132:135], v[172:175], 0
	v_mfma_f32_16x16x32_bf16 v[104:107], v[112:115], v[180:183], 0
	v_mfma_f32_16x16x32_bf16 v[96:99], v[132:135], v[180:183], 0
	v_mfma_f32_16x16x32_bf16 v[76:79], v[112:115], v[188:191], 0
	v_mfma_f32_16x16x32_bf16 v[72:75], v[132:135], v[188:191], 0
	v_mfma_f32_16x16x32_bf16 v[152:155], v[120:123], v[168:171], v[152:155]
	v_mfma_f32_16x16x32_bf16 v[148:151], v[144:147], v[168:171], v[148:151]
	v_mfma_f32_16x16x32_bf16 v[128:131], v[120:123], v[176:179], v[128:131]
	v_mfma_f32_16x16x32_bf16 v[124:127], v[144:147], v[176:179], v[124:127]
	v_mfma_f32_16x16x32_bf16 v[104:107], v[120:123], v[184:187], v[104:107]
	v_mfma_f32_16x16x32_bf16 v[96:99], v[144:147], v[184:187], v[96:99]
	v_mfma_f32_16x16x32_bf16 v[76:79], v[120:123], v[208:211], v[76:79]
	v_mfma_f32_16x16x32_bf16 v[72:75], v[144:147], v[208:211], v[72:75]
	s_setprio 0
	s_barrier
	v_lshl_add_u64 v[198:199], s[28:29], 0, v[192:193]
	s_add_i32 m0, s39, 0x10000
	ds_read_b128 v[156:159], v236 offset:16384
	ds_read_b128 v[168:171], v236 offset:17408
	ds_read_b128 v[172:175], v236 offset:18432
	ds_read_b128 v[176:179], v236 offset:19456
	ds_read_b128 v[180:183], v236 offset:20480
	ds_read_b128 v[184:187], v236 offset:21504
	ds_read_b128 v[188:191], v236 offset:22528
	ds_read_b128 v[208:211], v236 offset:23552
	global_load_lds_dwordx4 v[198:199], off
	s_add_i32 m0, s39, 0x12000
	v_lshl_add_u64 v[212:213], s[28:29], 0, v[202:203]
	global_load_lds_dwordx4 v[212:213], off
	v_lshl_add_u64 v[214:215], v[198:199], 0, s[100:101]
	s_add_i32 m0, s39, 0x14000
	v_lshl_add_u64 v[216:217], s[30:31], 0, v[194:195]
	global_load_lds_dwordx4 v[214:215], off
	s_add_i32 m0, s39, 0x16000
	v_lshl_add_u64 v[214:215], v[212:213], 0, s[100:101]
	global_load_lds_dwordx4 v[214:215], off
	s_mov_b32 m0, s40
	v_lshl_add_u64 v[214:215], s[30:31], 0, v[0:1]
	global_load_lds_dwordx4 v[214:215], off
	s_mov_b32 m0, s41
	s_add_i32 s54, 0, 0x18000
	global_load_lds_dwordx4 v[216:217], off
	s_waitcnt vmcnt(8) lgkmcnt(0)
	s_barrier
	s_setprio 1
	v_mfma_f32_16x16x32_bf16 v[64:67], v[68:71], v[156:159], 0
	v_mfma_f32_16x16x32_bf16 v[60:63], v[92:95], v[156:159], 0
	v_mfma_f32_16x16x32_bf16 v[48:51], v[68:71], v[172:175], 0
	v_mfma_f32_16x16x32_bf16 v[44:47], v[92:95], v[172:175], 0
	v_mfma_f32_16x16x32_bf16 v[32:35], v[68:71], v[180:183], 0
	v_mfma_f32_16x16x32_bf16 v[28:31], v[92:95], v[180:183], 0
	v_mfma_f32_16x16x32_bf16 v[16:19], v[68:71], v[188:191], 0
	v_mfma_f32_16x16x32_bf16 v[12:15], v[92:95], v[188:191], 0
	v_mfma_f32_16x16x32_bf16 v[64:67], v[80:83], v[168:171], v[64:67]
	v_mfma_f32_16x16x32_bf16 v[60:63], v[100:103], v[168:171], v[60:63]
	v_mfma_f32_16x16x32_bf16 v[48:51], v[80:83], v[176:179], v[48:51]
	v_mfma_f32_16x16x32_bf16 v[44:47], v[100:103], v[176:179], v[44:47]
	v_mfma_f32_16x16x32_bf16 v[32:35], v[80:83], v[184:187], v[32:35]
	v_mfma_f32_16x16x32_bf16 v[28:31], v[100:103], v[184:187], v[28:31]
	v_mfma_f32_16x16x32_bf16 v[16:19], v[80:83], v[208:211], v[16:19]
	v_mfma_f32_16x16x32_bf16 v[12:15], v[100:103], v[208:211], v[12:15]
	s_setprio 0
	s_setprio 1
	v_mfma_f32_16x16x32_bf16 v[56:59], v[112:115], v[156:159], 0
	v_mfma_f32_16x16x32_bf16 v[52:55], v[132:135], v[156:159], 0
	v_mfma_f32_16x16x32_bf16 v[40:43], v[112:115], v[172:175], 0
	v_mfma_f32_16x16x32_bf16 v[36:39], v[132:135], v[172:175], 0
	v_mfma_f32_16x16x32_bf16 v[24:27], v[112:115], v[180:183], 0
	v_mfma_f32_16x16x32_bf16 v[20:23], v[132:135], v[180:183], 0
	v_mfma_f32_16x16x32_bf16 v[8:11], v[112:115], v[188:191], 0
	v_mfma_f32_16x16x32_bf16 v[4:7], v[132:135], v[188:191], 0
	v_mfma_f32_16x16x32_bf16 v[56:59], v[120:123], v[168:171], v[56:59]
	v_mfma_f32_16x16x32_bf16 v[52:55], v[144:147], v[168:171], v[52:55]
	v_mfma_f32_16x16x32_bf16 v[40:43], v[120:123], v[176:179], v[40:43]
	v_mfma_f32_16x16x32_bf16 v[36:39], v[144:147], v[176:179], v[36:39]
	v_mfma_f32_16x16x32_bf16 v[24:27], v[120:123], v[184:187], v[24:27]
	v_mfma_f32_16x16x32_bf16 v[20:23], v[144:147], v[184:187], v[20:23]
	v_mfma_f32_16x16x32_bf16 v[8:11], v[120:123], v[208:211], v[8:11]
	v_mfma_f32_16x16x32_bf16 v[4:7], v[144:147], v[208:211], v[4:7]
	s_setprio 0
	s_barrier
	s_branch .Lkmid_3
; #define PG8_STAGE(bufoff, gbase, voff) do { _Pragma("unroll") for (int _i = 0; _i < 2; ++_i) \
;         __builtin_amdgcn_global_load_lds((const unsigned*)((const char*)(gbase) + (voff)[_i]), (PG8_LAS unsigned*)(lds + (bufoff) + ldsw + _i * 8192), 16, 0, 0); } while (0)
; #define PG8_LDA(dst, b, h) do { _Pragma("unroll") for (int m = 0; m < 4; ++m) _Pragma("unroll") for (int k = 0; k < 2; ++k) dst[m][k] = *(const PG8_LAS bf16x8*)(lds + PG8_SA(b, h) + aoff + m * 2048 + k * 1024); } while (0)
; #define PG8_LDB(dst, b, h) do { _Pragma("unroll") for (int n = 0; n < 2; ++n) _Pragma("unroll") for (int k = 0; k < 2; ++k) dst[n][k] = *(const PG8_LAS bf16x8*)(lds + PG8_SB(b, h) + boff + n * 2048 + k * 1024); } while (0)
; #define PG8_MMA(ai, bj, At, Bt) do { __builtin_amdgcn_s_setprio(1); _Pragma("unroll") for (int m = 0; m < 4; ++m) _Pragma("unroll") for (int n = 0; n < 2; ++n) _Pragma("unroll") for (int k = 0; k < 2; ++k) \
;         acc[ai][bj][m][n] = __builtin_amdgcn_mfma_f32_16x16x32_bf16(Bt[n][k], At[m][k], acc[ai][bj][m][n], 0, 0, 0); __builtin_amdgcn_s_setprio(0); } while (0)
; #define PG8_WAIT_V(n) asm volatile("s_waitcnt vmcnt(" #n ")" ::: "memory")
; #define PG8_BAR __builtin_amdgcn_s_barrier()
; template <class Epi, class Sched, bool ALIGN_EPI = false, bool SP2 = false>
; __device__ __forceinline__ void gemm_phase(PG8_LAS unsigned char* lds, const Gemm g, const Sched& S, const Epi& E) {
;     ...
;         for (int t = 0; t < nt; t += 2) {
;             const bool last = (t == nt - 2);
;             const char* a1 = cA + (size_t)(t + 1) * kstep;
;             const char* a2 = last ? nA : cA + (size_t)(t + 2) * kstep; const char* b2 = last ? nB : cB + (size_t)(t + 2) * kstep;
;             const char* a3 = a2 + kstep; const char* b3 = b2 + kstep;
;             if (last && has_next) S.a_ready(nxt);
;             if constexpr (SP2) {
;             PG8_LDB(B0, 0, 0); PG8_LDB(B1, 0, 1); PG8_SCHED; PG8_LDA(At, 0, 0); PG8_STAGE(PG8_SA(1, 1), a1 + hstep, voffA);
;             PG8_WAIT_V(8); PG8_WAIT_L(0); PG8_BAR; PG8_MMA(0, 0, At, B0); PG8_MMA(0, 1, At, B1); PG8_BAR; PG8_SCHED;
;             PG8_LDA(At, 0, 1); PG8_STAGE(PG8_SB(0, 0), b2, voffB); PG8_STAGE(PG8_SB(0, 1), b2 + hstep, voffB); PG8_STAGE(PG8_SA(0, 0), a2, voffA);
;             PG8_WAIT_V(8); PG8_WAIT_L(0); PG8_BAR; PG8_MMA(1, 0, At, B0); PG8_MMA(1, 1, At, B1); PG8_BAR; PG8_SCHED;
.LBB0_480:
	s_add_u32 s8, s26, 0x100
	s_addc_u32 s9, s27, 0
	s_cmp_eq_u32 s53, 40
	s_cselect_b32 s31, s23, s9
	s_cselect_b32 s30, s22, s8
	s_cselect_b32 s29, s25, s45
	s_cselect_b32 s28, s24, s44
	ds_read_b128 v[68:71], v234
	ds_read_b128 v[80:83], v234 offset:1024
	ds_read_b128 v[92:95], v234 offset:2048
	ds_read_b128 v[100:103], v234 offset:3072
	ds_read_b128 v[112:115], v234 offset:16384
	ds_read_b128 v[120:123], v234 offset:17408
	ds_read_b128 v[132:135], v234 offset:18432
	ds_read_b128 v[144:147], v234 offset:19456
	v_lshl_add_u64 v[198:199], s[26:27], 0, v[204:205]
	s_add_i32 m0, s40, 0xc000
	ds_read_b128 v[156:159], v236
	ds_read_b128 v[168:171], v236 offset:1024
	ds_read_b128 v[172:175], v236 offset:2048
	ds_read_b128 v[176:179], v236 offset:3072
	ds_read_b128 v[180:183], v236 offset:4096
	ds_read_b128 v[184:187], v236 offset:5120
	ds_read_b128 v[188:191], v236 offset:6144
	ds_read_b128 v[208:211], v236 offset:7168
	global_load_lds_dwordx4 v[198:199], off
	s_add_i32 m0, s40, 0xe000
	v_lshl_add_u64 v[198:199], s[26:27], 0, v[206:207]
	global_load_lds_dwordx4 v[198:199], off
	s_waitcnt vmcnt(8) lgkmcnt(0)
	s_barrier
	s_setprio 1
	v_mfma_f32_16x16x32_bf16 v[164:167], v[68:71], v[156:159], v[164:167]
	v_mfma_f32_16x16x32_bf16 v[160:163], v[92:95], v[156:159], v[160:163]
	v_mfma_f32_16x16x32_bf16 v[140:143], v[68:71], v[172:175], v[140:143]
	v_mfma_f32_16x16x32_bf16 v[136:139], v[92:95], v[172:175], v[136:139]
	v_mfma_f32_16x16x32_bf16 v[116:119], v[68:71], v[180:183], v[116:119]
	v_mfma_f32_16x16x32_bf16 v[108:111], v[92:95], v[180:183], v[108:111]
	v_mfma_f32_16x16x32_bf16 v[88:91], v[68:71], v[188:191], v[88:91]
	v_mfma_f32_16x16x32_bf16 v[84:87], v[92:95], v[188:191], v[84:87]
	v_mfma_f32_16x16x32_bf16 v[164:167], v[80:83], v[168:171], v[164:167]
	v_mfma_f32_16x16x32_bf16 v[160:163], v[100:103], v[168:171], v[160:163]
	v_mfma_f32_16x16x32_bf16 v[140:143], v[80:83], v[176:179], v[140:143]
	v_mfma_f32_16x16x32_bf16 v[136:139], v[100:103], v[176:179], v[136:139]
	v_mfma_f32_16x16x32_bf16 v[116:119], v[80:83], v[184:187], v[116:119]
	v_mfma_f32_16x16x32_bf16 v[108:111], v[100:103], v[184:187], v[108:111]
	v_mfma_f32_16x16x32_bf16 v[88:91], v[80:83], v[208:211], v[88:91]
	v_mfma_f32_16x16x32_bf16 v[84:87], v[100:103], v[208:211], v[84:87]
	s_setprio 0
	s_setprio 1
	v_mfma_f32_16x16x32_bf16 v[152:155], v[112:115], v[156:159], v[152:155]
	v_mfma_f32_16x16x32_bf16 v[148:151], v[132:135], v[156:159], v[148:151]
	v_mfma_f32_16x16x32_bf16 v[128:131], v[112:115], v[172:175], v[128:131]
	v_mfma_f32_16x16x32_bf16 v[124:127], v[132:135], v[172:175], v[124:127]
	v_mfma_f32_16x16x32_bf16 v[104:107], v[112:115], v[180:183], v[104:107]
	v_mfma_f32_16x16x32_bf16 v[96:99], v[132:135], v[180:183], v[96:99]
	v_mfma_f32_16x16x32_bf16 v[76:79], v[112:115], v[188:191], v[76:79]
	v_mfma_f32_16x16x32_bf16 v[72:75], v[132:135], v[188:191], v[72:75]
	v_mfma_f32_16x16x32_bf16 v[152:155], v[120:123], v[168:171], v[152:155]
	v_mfma_f32_16x16x32_bf16 v[148:151], v[144:147], v[168:171], v[148:151]
	v_mfma_f32_16x16x32_bf16 v[128:131], v[120:123], v[176:179], v[128:131]
	v_mfma_f32_16x16x32_bf16 v[124:127], v[144:147], v[176:179], v[124:127]
	v_mfma_f32_16x16x32_bf16 v[104:107], v[120:123], v[184:187], v[104:107]
	v_mfma_f32_16x16x32_bf16 v[96:99], v[144:147], v[184:187], v[96:99]
	v_mfma_f32_16x16x32_bf16 v[76:79], v[120:123], v[208:211], v[76:79]
	v_mfma_f32_16x16x32_bf16 v[72:75], v[144:147], v[208:211], v[72:75]
	s_setprio 0
	s_barrier
	v_lshl_add_u64 v[198:199], s[28:29], 0, v[192:193]
	s_add_i32 m0, s39, 0x10000
	ds_read_b128 v[156:159], v236 offset:16384
	ds_read_b128 v[168:171], v236 offset:17408
	ds_read_b128 v[172:175], v236 offset:18432
	ds_read_b128 v[176:179], v236 offset:19456
	ds_read_b128 v[180:183], v236 offset:20480
	ds_read_b128 v[184:187], v236 offset:21504
	ds_read_b128 v[188:191], v236 offset:22528
	ds_read_b128 v[208:211], v236 offset:23552
	global_load_lds_dwordx4 v[198:199], off
	s_add_i32 m0, s39, 0x12000
	v_lshl_add_u64 v[212:213], s[28:29], 0, v[202:203]
	global_load_lds_dwordx4 v[212:213], off
	v_lshl_add_u64 v[214:215], v[198:199], 0, s[100:101]
	s_add_i32 m0, s39, 0x14000
	v_lshl_add_u64 v[216:217], s[30:31], 0, v[194:195]
	global_load_lds_dwordx4 v[214:215], off
	s_add_i32 m0, s39, 0x16000
	v_lshl_add_u64 v[214:215], v[212:213], 0, s[100:101]
	global_load_lds_dwordx4 v[214:215], off
	s_mov_b32 m0, s40
	v_lshl_add_u64 v[214:215], s[30:31], 0, v[0:1]
	global_load_lds_dwordx4 v[214:215], off
	s_mov_b32 m0, s41
	s_add_i32 s54, 0, 0x18000
	global_load_lds_dwordx4 v[216:217], off
	s_waitcnt vmcnt(8) lgkmcnt(0)
	s_barrier
	s_setprio 1
	v_mfma_f32_16x16x32_bf16 v[64:67], v[68:71], v[156:159], v[64:67]
	v_mfma_f32_16x16x32_bf16 v[60:63], v[92:95], v[156:159], v[60:63]
	v_mfma_f32_16x16x32_bf16 v[48:51], v[68:71], v[172:175], v[48:51]
	v_mfma_f32_16x16x32_bf16 v[44:47], v[92:95], v[172:175], v[44:47]
	v_mfma_f32_16x16x32_bf16 v[32:35], v[68:71], v[180:183], v[32:35]
	v_mfma_f32_16x16x32_bf16 v[28:31], v[92:95], v[180:183], v[28:31]
	v_mfma_f32_16x16x32_bf16 v[16:19], v[68:71], v[188:191], v[16:19]
	v_mfma_f32_16x16x32_bf16 v[12:15], v[92:95], v[188:191], v[12:15]
	v_mfma_f32_16x16x32_bf16 v[64:67], v[80:83], v[168:171], v[64:67]
	v_mfma_f32_16x16x32_bf16 v[60:63], v[100:103], v[168:171], v[60:63]
	v_mfma_f32_16x16x32_bf16 v[48:51], v[80:83], v[176:179], v[48:51]
	v_mfma_f32_16x16x32_bf16 v[44:47], v[100:103], v[176:179], v[44:47]
	v_mfma_f32_16x16x32_bf16 v[32:35], v[80:83], v[184:187], v[32:35]
	v_mfma_f32_16x16x32_bf16 v[28:31], v[100:103], v[184:187], v[28:31]
	v_mfma_f32_16x16x32_bf16 v[16:19], v[80:83], v[208:211], v[16:19]
	v_mfma_f32_16x16x32_bf16 v[12:15], v[100:103], v[208:211], v[12:15]
	s_setprio 0
	s_setprio 1
	v_mfma_f32_16x16x32_bf16 v[56:59], v[112:115], v[156:159], v[56:59]
	v_mfma_f32_16x16x32_bf16 v[52:55], v[132:135], v[156:159], v[52:55]
	v_mfma_f32_16x16x32_bf16 v[40:43], v[112:115], v[172:175], v[40:43]
	v_mfma_f32_16x16x32_bf16 v[36:39], v[132:135], v[172:175], v[36:39]
	v_mfma_f32_16x16x32_bf16 v[24:27], v[112:115], v[180:183], v[24:27]
	v_mfma_f32_16x16x32_bf16 v[20:23], v[132:135], v[180:183], v[20:23]
	v_mfma_f32_16x16x32_bf16 v[8:11], v[112:115], v[188:191], v[8:11]
	v_mfma_f32_16x16x32_bf16 v[4:7], v[132:135], v[188:191], v[4:7]
	v_mfma_f32_16x16x32_bf16 v[56:59], v[120:123], v[168:171], v[56:59]
	v_mfma_f32_16x16x32_bf16 v[52:55], v[144:147], v[168:171], v[52:55]
	v_mfma_f32_16x16x32_bf16 v[40:43], v[120:123], v[176:179], v[40:43]
	v_mfma_f32_16x16x32_bf16 v[36:39], v[144:147], v[176:179], v[36:39]
	v_mfma_f32_16x16x32_bf16 v[24:27], v[120:123], v[184:187], v[24:27]
	v_mfma_f32_16x16x32_bf16 v[20:23], v[144:147], v[184:187], v[20:23]
	v_mfma_f32_16x16x32_bf16 v[8:11], v[120:123], v[208:211], v[8:11]
	v_mfma_f32_16x16x32_bf16 v[4:7], v[144:147], v[208:211], v[4:7]
	s_setprio 0
	s_barrier
; #define PG8_STAGE(bufoff, gbase, voff) do { _Pragma("unroll") for (int _i = 0; _i < 2; ++_i) \
;         __builtin_amdgcn_global_load_lds((const unsigned*)((const char*)(gbase) + (voff)[_i]), (PG8_LAS unsigned*)(lds + (bufoff) + ldsw + _i * 8192), 16, 0, 0); } while (0)
; #define PG8_LDA(dst, b, h) do { _Pragma("unroll") for (int m = 0; m < 4; ++m) _Pragma("unroll") for (int k = 0; k < 2; ++k) dst[m][k] = *(const PG8_LAS bf16x8*)(lds + PG8_SA(b, h) + aoff + m * 2048 + k * 1024); } while (0)
; #define PG8_LDB(dst, b, h) do { _Pragma("unroll") for (int n = 0; n < 2; ++n) _Pragma("unroll") for (int k = 0; k < 2; ++k) dst[n][k] = *(const PG8_LAS bf16x8*)(lds + PG8_SB(b, h) + boff + n * 2048 + k * 1024); } while (0)
; template <class Epi, class Sched, bool ALIGN_EPI = false, bool SP2 = false>
; __device__ __forceinline__ void gemm_phase(PG8_LAS unsigned char* lds, const Gemm g, const Sched& S, const Epi& E) {
;     ...
;         for (int t = 0; t < nt; t += 2) {
;             const bool last = (t == nt - 2);
;             const char* a1 = cA + (size_t)(t + 1) * kstep;
;             const char* a2 = last ? nA : cA + (size_t)(t + 2) * kstep; const char* b2 = last ? nB : cB + (size_t)(t + 2) * kstep;
;             const char* a3 = a2 + kstep; const char* b3 = b2 + kstep;
;             if (last && has_next) S.a_ready(nxt);
;             if constexpr (SP2) {
;             PG8_LDB(B0, 0, 0); PG8_LDB(B1, 0, 1); PG8_SCHED; PG8_LDA(At, 0, 0); PG8_STAGE(PG8_SA(1, 1), a1 + hstep, voffA);
;             PG8_WAIT_V(8); PG8_WAIT_L(0); PG8_BAR; PG8_MMA(0, 0, At, B0); PG8_MMA(0, 1, At, B1); PG8_BAR; PG8_SCHED;
;             PG8_LDA(At, 0, 1); PG8_STAGE(PG8_SB(0, 0), b2, voffB); PG8_STAGE(PG8_SB(0, 1), b2 + hstep, voffB); PG8_STAGE(PG8_SA(0, 0), a2, voffA);
;             PG8_WAIT_V(8); PG8_WAIT_L(0); PG8_BAR; PG8_MMA(1, 0, At, B0); PG8_MMA(1, 1, At, B1); PG8_BAR; PG8_SCHED;
;             PG8_LDB(B0, 1, 0); PG8_LDB(B1, 1, 1); PG8_SCHED; PG8_LDA(At, 1, 0); PG8_STAGE(PG8_SA(0, 1), a2 + hstep, voffA);
;             PG8_WAIT_V(8); PG8_WAIT_L(0); PG8_BAR; PG8_MMA(0, 0, At, B0); PG8_MMA(0, 1, At, B1); PG8_BAR; PG8_SCHED;
;             PG8_LDA(At, 1, 1); PG8_STAGE(PG8_SB(1, 0), b3, voffB); PG8_STAGE(PG8_SB(1, 1), b3 + hstep, voffB); PG8_STAGE(PG8_SA(1, 0), a3, voffA);
;             PG8_WAIT_V(8); PG8_WAIT_L(0); PG8_BAR; PG8_MMA(1, 0, At, B0); PG8_MMA(1, 1, At, B1); PG8_BAR; PG8_SCHED;
.Lkmid_3:
	ds_read_b128 v[68:71], v234 offset:32768
	ds_read_b128 v[80:83], v234 offset:33792
	ds_read_b128 v[92:95], v234 offset:34816
	ds_read_b128 v[100:103], v234 offset:35840
	ds_read_b128 v[112:115], v234 offset:49152
	ds_read_b128 v[120:123], v234 offset:50176
	ds_read_b128 v[132:135], v234 offset:51200
	ds_read_b128 v[144:147], v234 offset:52224
	s_mov_b32 m0, s42
	v_lshl_add_u64 v[218:219], v[214:215], 0, s[100:101]
	ds_read_b128 v[156:159], v236 offset:32768
	ds_read_b128 v[168:171], v236 offset:33792
	ds_read_b128 v[172:175], v236 offset:34816
	ds_read_b128 v[176:179], v236 offset:35840
	ds_read_b128 v[180:183], v236 offset:36864
	ds_read_b128 v[184:187], v236 offset:37888
	ds_read_b128 v[188:191], v236 offset:38912
	ds_read_b128 v[208:211], v236 offset:39936
	global_load_lds_dwordx4 v[218:219], off
	s_mov_b32 m0, s43
	v_lshl_add_u64 v[218:219], v[216:217], 0, s[100:101]
	global_load_lds_dwordx4 v[218:219], off
	s_waitcnt vmcnt(8) lgkmcnt(0)
	s_barrier
	s_setprio 1
	v_mfma_f32_16x16x32_bf16 v[164:167], v[68:71], v[156:159], v[164:167]
	v_mfma_f32_16x16x32_bf16 v[160:163], v[92:95], v[156:159], v[160:163]
	v_mfma_f32_16x16x32_bf16 v[140:143], v[68:71], v[172:175], v[140:143]
	v_mfma_f32_16x16x32_bf16 v[136:139], v[92:95], v[172:175], v[136:139]
	v_mfma_f32_16x16x32_bf16 v[116:119], v[68:71], v[180:183], v[116:119]
	v_mfma_f32_16x16x32_bf16 v[108:111], v[92:95], v[180:183], v[108:111]
	v_mfma_f32_16x16x32_bf16 v[88:91], v[68:71], v[188:191], v[88:91]
	v_mfma_f32_16x16x32_bf16 v[84:87], v[92:95], v[188:191], v[84:87]
	v_mfma_f32_16x16x32_bf16 v[164:167], v[80:83], v[168:171], v[164:167]
	v_mfma_f32_16x16x32_bf16 v[160:163], v[100:103], v[168:171], v[160:163]
	v_mfma_f32_16x16x32_bf16 v[140:143], v[80:83], v[176:179], v[140:143]
	v_mfma_f32_16x16x32_bf16 v[136:139], v[100:103], v[176:179], v[136:139]
	v_mfma_f32_16x16x32_bf16 v[116:119], v[80:83], v[184:187], v[116:119]
	v_mfma_f32_16x16x32_bf16 v[108:111], v[100:103], v[184:187], v[108:111]
	v_mfma_f32_16x16x32_bf16 v[88:91], v[80:83], v[208:211], v[88:91]
	v_mfma_f32_16x16x32_bf16 v[84:87], v[100:103], v[208:211], v[84:87]
	s_setprio 0
	s_setprio 1
	v_mfma_f32_16x16x32_bf16 v[152:155], v[112:115], v[156:159], v[152:155]
	v_mfma_f32_16x16x32_bf16 v[148:151], v[132:135], v[156:159], v[148:151]
	v_mfma_f32_16x16x32_bf16 v[128:131], v[112:115], v[172:175], v[128:131]
	v_mfma_f32_16x16x32_bf16 v[124:127], v[132:135], v[172:175], v[124:127]
	v_mfma_f32_16x16x32_bf16 v[104:107], v[112:115], v[180:183], v[104:107]
	v_mfma_f32_16x16x32_bf16 v[96:99], v[132:135], v[180:183], v[96:99]
	v_mfma_f32_16x16x32_bf16 v[76:79], v[112:115], v[188:191], v[76:79]
	v_mfma_f32_16x16x32_bf16 v[72:75], v[132:135], v[188:191], v[72:75]
	v_mfma_f32_16x16x32_bf16 v[152:155], v[120:123], v[168:171], v[152:155]
	v_mfma_f32_16x16x32_bf16 v[148:151], v[144:147], v[168:171], v[148:151]
	v_mfma_f32_16x16x32_bf16 v[128:131], v[120:123], v[176:179], v[128:131]
	v_mfma_f32_16x16x32_bf16 v[124:127], v[144:147], v[176:179], v[124:127]
	v_mfma_f32_16x16x32_bf16 v[104:107], v[120:123], v[184:187], v[104:107]
	v_mfma_f32_16x16x32_bf16 v[96:99], v[144:147], v[184:187], v[96:99]
	v_mfma_f32_16x16x32_bf16 v[76:79], v[120:123], v[208:211], v[76:79]
	v_mfma_f32_16x16x32_bf16 v[72:75], v[144:147], v[208:211], v[72:75]
	s_setprio 0
	s_barrier
	s_add_i32 m0, s39, 0x17f80
	ds_read_b128 v[156:159], v236 offset:49152
	ds_read_b128 v[168:171], v236 offset:50176
	ds_read_b128 v[172:175], v236 offset:51200
	ds_read_b128 v[176:179], v236 offset:52224
	ds_read_b128 v[180:183], v236 offset:53248
	ds_read_b128 v[184:187], v236 offset:54272
	ds_read_b128 v[188:191], v236 offset:55296
	ds_read_b128 v[208:211], v236 offset:56320
	global_load_lds_dwordx4 v[198:199], off offset:128
	s_add_i32 m0, s39, 0x19f80
	v_lshl_add_u64 v[198:199], v[198:199], 0, s[100:101]
	global_load_lds_dwordx4 v[212:213], off offset:128
	s_add_i32 m0, s39, 0x1bf80
	v_lshl_add_u64 v[218:219], v[212:213], 0, s[100:101]
	global_load_lds_dwordx4 v[198:199], off offset:128
	s_add_i32 m0, s39, 0x1df80
	s_add_i32 s53, s53, 2
	global_load_lds_dwordx4 v[218:219], off offset:128
	s_add_i32 m0, s47, 0xffffff80
	s_add_u32 s44, s44, 0x100
	s_addc_u32 s45, s45, 0
	global_load_lds_dwordx4 v[214:215], off offset:128
	s_add_i32 m0, s48, 0xffffff80
	s_mov_b64 s[26:27], s[8:9]
	global_load_lds_dwordx4 v[216:217], off offset:128
	s_waitcnt vmcnt(8) lgkmcnt(0)
	s_barrier
	s_setprio 1
	v_mfma_f32_16x16x32_bf16 v[64:67], v[68:71], v[156:159], v[64:67]
	v_mfma_f32_16x16x32_bf16 v[60:63], v[92:95], v[156:159], v[60:63]
	v_mfma_f32_16x16x32_bf16 v[48:51], v[68:71], v[172:175], v[48:51]
	v_mfma_f32_16x16x32_bf16 v[44:47], v[92:95], v[172:175], v[44:47]
	v_mfma_f32_16x16x32_bf16 v[32:35], v[68:71], v[180:183], v[32:35]
	v_mfma_f32_16x16x32_bf16 v[28:31], v[92:95], v[180:183], v[28:31]
	v_mfma_f32_16x16x32_bf16 v[16:19], v[68:71], v[188:191], v[16:19]
	v_mfma_f32_16x16x32_bf16 v[12:15], v[92:95], v[188:191], v[12:15]
	v_mfma_f32_16x16x32_bf16 v[64:67], v[80:83], v[168:171], v[64:67]
	v_mfma_f32_16x16x32_bf16 v[60:63], v[100:103], v[168:171], v[60:63]
	v_mfma_f32_16x16x32_bf16 v[48:51], v[80:83], v[176:179], v[48:51]
	v_mfma_f32_16x16x32_bf16 v[44:47], v[100:103], v[176:179], v[44:47]
	v_mfma_f32_16x16x32_bf16 v[32:35], v[80:83], v[184:187], v[32:35]
	v_mfma_f32_16x16x32_bf16 v[28:31], v[100:103], v[184:187], v[28:31]
	v_mfma_f32_16x16x32_bf16 v[16:19], v[80:83], v[208:211], v[16:19]
	v_mfma_f32_16x16x32_bf16 v[12:15], v[100:103], v[208:211], v[12:15]
	s_setprio 0
	s_setprio 1
	v_mfma_f32_16x16x32_bf16 v[56:59], v[112:115], v[156:159], v[56:59]
	v_mfma_f32_16x16x32_bf16 v[52:55], v[132:135], v[156:159], v[52:55]
	v_mfma_f32_16x16x32_bf16 v[40:43], v[112:115], v[172:175], v[40:43]
	v_mfma_f32_16x16x32_bf16 v[36:39], v[132:135], v[172:175], v[36:39]
	v_mfma_f32_16x16x32_bf16 v[24:27], v[112:115], v[180:183], v[24:27]
	v_mfma_f32_16x16x32_bf16 v[20:23], v[132:135], v[180:183], v[20:23]
	v_mfma_f32_16x16x32_bf16 v[8:11], v[112:115], v[188:191], v[8:11]
	v_mfma_f32_16x16x32_bf16 v[4:7], v[132:135], v[188:191], v[4:7]
	v_mfma_f32_16x16x32_bf16 v[56:59], v[120:123], v[168:171], v[56:59]
	v_mfma_f32_16x16x32_bf16 v[52:55], v[144:147], v[168:171], v[52:55]
	v_mfma_f32_16x16x32_bf16 v[40:43], v[120:123], v[176:179], v[40:43]
	v_mfma_f32_16x16x32_bf16 v[36:39], v[144:147], v[176:179], v[36:39]
	v_mfma_f32_16x16x32_bf16 v[24:27], v[120:123], v[184:187], v[24:27]
	v_mfma_f32_16x16x32_bf16 v[20:23], v[144:147], v[184:187], v[20:23]
	v_mfma_f32_16x16x32_bf16 v[8:11], v[120:123], v[208:211], v[8:11]
	v_mfma_f32_16x16x32_bf16 v[4:7], v[144:147], v[208:211], v[4:7]
	s_setprio 0
	s_barrier
	s_cmp_gt_u32 s53, 41
	s_cbranch_scc0 .LBB0_480
	s_and_b64 vcc, exec, s[20:21]
	s_cbranch_vccz .LBB0_483
	s_barrier
